# v47 plus 30 redundant up-proj epilogue waits (vmcnt/lgkmcnt after already-waited hoisted gain loads) removed
# baseline (speedup 1.0000x reference)
; #define SBAR() __builtin_amdgcn_sched_barrier(0)
; DEV int opaque_tid() { int t = threadIdx.x; asm volatile("" : "+v"(t)); return t; }
; DEV void glds16(const u16* g, char* l) { __builtin_amdgcn_global_load_lds((const unsigned*)g, (unsigned*)l, 16, 0, 0); }
; template <int WM, int WN, int BN, int EPI>
; DEV void gemm_tile(const u16* __restrict__ A, int lda, const u16* __restrict__ Bt, int ldb, int K, int m0, char* lds,
;                    const Params& P, int layer, int batch, int nt) {
;     ...
;   const int tid = opaque_tid(), wid = tid >> 6, lane = tid & 63, r32 = lane & 31, hi = lane >> 5;
;   const int wm = wid / WN, wn = wid % WN;
;   char* As = lds; char* Bs = lds + 65536;
;   f32x16 acc[MI][NI];
; #pragma unroll
;   for (int mi = 0; mi < MI; ++mi)
; #pragma unroll
;     for (int ni = 0; ni < NI; ++ni) acc[mi][ni] = f32x16{};
;   const int srow = tid >> 3, sch = (tid & 7) ^ ((srow >> 1) & 7);
;   const u16* Ap = A + (long)(m0 + srow) * lda + sch * 8;
;   const u16* Bp = Bt + (long)srow * ldb + sch * 8;
;   const int soff = tid * 16;
;     ...
;   GLOAD(0, 0); asm volatile("s_waitcnt vmcnt(0)" ::: "memory"); __syncthreads();
;   const int nk = K >> 6;
;   for (int kt = 0; kt < nk; ++kt) {
;     const bool more = kt + 1 < nk;
;     const int nb = (kt + 1) & 1;
;     const char* as = As + (kt & 1) * 32768; const char* bs = Bs + (kt & 1) * 32768;
; #pragma unroll
;     for (int ks = 0; ks < 4; ++ks) {
;       if (more) { glds16(Ap + (long)ks * 64 * lda + (kt + 1) * 64, As + nb * 32768 + soff + ks * 8192);
;                   if (ks < NB) glds16(Bp + (long)ks * 64 * ldb + (kt + 1) * 64, Bs + nb * 32768 + soff + ks * 8192); }
;       SBAR();
;       bf16x8 xf[MI], wf[NI];
; #pragma unroll
;       for (int mi = 0; mi < MI; ++mi) xf[mi] = *reinterpret_cast<const bf16x8*>(as + swz128(wm * (MI * 32) + mi * 32 + r32, ks * 2 + hi));
; #pragma unroll
;       for (int ni = 0; ni < NI; ++ni) wf[ni] = *reinterpret_cast<const bf16x8*>(bs + swz128(wn * (NI * 32) + ni * 32 + r32, ks * 2 + hi));
; #pragma unroll
;       for (int mi = 0; mi < MI; ++mi)
; #pragma unroll
;         for (int ni = 0; ni < NI; ++ni) acc[mi][ni] = __builtin_amdgcn_mfma_f32_32x32x16_bf16(wf[ni], xf[mi], acc[mi][ni], 0, 0, 0);
;     }
.LBB0_358:
	s_mul_i32 s2, s54, 0xc0
	s_mul_i32 s3, s51, 0x300
	s_add_i32 s3, s2, s3
	s_lshl_b32 s3, s3, 9
	s_add_u32 s60, s36, s3
	s_addc_u32 s61, s38, 0
	s_lshl_b32 s3, s55, 8
	v_mov_b32_e32 v100, v226
	s_and_b32 s3, s3, 0x3f00
	s_add_i32 s22, 0, 0x10000
	v_ashrrev_i32_e32 v0, 3, v100
	v_lshrrev_b32_e32 v1, 4, v100
	v_add_u32_e32 v2, s3, v0
	v_xor_b32_e32 v1, v1, v100
	v_ashrrev_i32_e32 v3, 31, v2
	v_lshlrev_b32_e32 v5, 4, v100
	v_lshlrev_b64 v[2:3], 9, v[2:3]
	v_lshlrev_b32_e32 v1, 4, v1
	v_add_u32_e32 v120, 0, v5
	v_lshl_add_u64 v[2:3], s[6:7], 0, v[2:3]
	v_and_b32_e32 v184, 0x70, v1
	v_readfirstlane_b32 s82, v120
	v_add_u32_e32 v6, 0x2000, v120
	v_lshl_add_u64 v[96:97], v[2:3], 0, v[184:185]
	v_ashrrev_i32_e32 v1, 31, v0
	s_mov_b32 m0, s82
	v_readfirstlane_b32 s79, v6
	v_add_u32_e32 v6, 0x4000, v120
	v_lshlrev_b64 v[0:1], 9, v[0:1]
	global_load_lds_dwordx4 v[96:97], off
	v_lshl_add_u64 v[2:3], v[96:97], 0, s[40:41]
	s_mov_b32 m0, s79
	v_readfirstlane_b32 s65, v6
	v_lshl_add_u64 v[0:1], s[60:61], 0, v[0:1]
	global_load_lds_dwordx4 v[2:3], off
	v_lshl_add_u64 v[2:3], v[96:97], 0, s[28:29]
	s_mov_b32 m0, s65
	s_mov_b64 s[60:61], 0x18000
	v_add_u32_e32 v6, 0x6000, v120
	global_load_lds_dwordx4 v[2:3], off
	v_lshl_add_u64 v[2:3], v[96:97], 0, s[60:61]
	v_readfirstlane_b32 s60, v6
	s_mov_b32 m0, s60
	v_add_u32_e32 v121, s22, v5
	global_load_lds_dwordx4 v[2:3], off
	v_readfirstlane_b32 s81, v121
	v_add_u32_e32 v2, 0x2000, v121
	v_lshl_add_u64 v[98:99], v[0:1], 0, v[184:185]
	s_mov_b32 m0, s81
	v_readfirstlane_b32 s75, v2
	v_add_u32_e32 v2, 0x4000, v121
	global_load_lds_dwordx4 v[98:99], off
	v_lshl_add_u64 v[0:1], v[98:99], 0, s[40:41]
	s_mov_b32 m0, s75
	v_readfirstlane_b32 s61, v2
	v_and_b32_e32 v101, 31, v100
	global_load_lds_dwordx4 v[0:1], off
	v_lshl_add_u64 v[0:1], v[98:99], 0, s[28:29]
	s_mov_b32 m0, s61
	v_add_u32_e32 v5, 0x8000, v120
	v_ashrrev_i32_e32 v103, 6, v100
	global_load_lds_dwordx4 v[0:1], off
	v_lshlrev_b32_e32 v1, 7, v101
	v_add_u32_e32 v6, 0x8000, v121
	v_readfirstlane_b32 s62, v5
	v_lshlrev_b32_e32 v0, 12, v103
	v_add_u32_e32 v124, s22, v1
	v_lshl_add_u64 v[2:3], v[96:97], 0, s[30:31]
	s_mov_b32 m0, s62
	v_readfirstlane_b32 s22, v6
	s_waitcnt vmcnt(0)
	s_waitcnt vmcnt(0) lgkmcnt(0)
	s_barrier
	v_add3_u32 v123, 0, v0, v1
	v_lshl_add_u64 v[0:1], v[98:99], 0, s[30:31]
	global_load_lds_dwordx4 v[2:3], off
	s_mov_b32 m0, s22
	v_lshrrev_b32_e32 v4, 5, v100
	global_load_lds_dwordx4 v[0:1], off
	v_bfe_u32 v102, v100, 5, 1
	v_bfe_u32 v122, v100, 1, 3
	v_bitop3_b32 v0, v4, v122, 1 bitop3:0x6c
	v_lshlrev_b32_e32 v4, 4, v0
	v_add_u32_e32 v104, v124, v4
	ds_read_b128 v[194:197], v104
	v_add_u32_e32 v125, v123, v4
	ds_read_b128 v[198:201], v125
	ds_read_b128 v[202:205], v104 offset:4096
	ds_read_b128 v[206:209], v104 offset:8192
	ds_read_b128 v[210:213], v104 offset:12288
	ds_read_b128 v[214:217], v104 offset:16384
	ds_read_b128 v[218:221], v104 offset:20480
	v_add_u32_e32 v26, 0xa000, v121
	v_lshl_add_u64 v[24:25], v[96:97], 0, s[42:43]
	v_readfirstlane_b32 s63, v26
	s_waitcnt lgkmcnt(5)
	v_mfma_f32_32x32x16_bf16 v[80:95], v[194:197], v[198:201], 0
	s_waitcnt lgkmcnt(3)
	v_mfma_f32_32x32x16_bf16 v[64:79], v[202:205], v[198:201], 0
	v_mfma_f32_32x32x16_bf16 v[48:63], v[206:209], v[198:201], 0
	s_waitcnt lgkmcnt(0)
	v_mfma_f32_32x32x16_bf16 v[32:47], v[210:213], v[198:201], 0
	v_add_u32_e32 v0, 0xa000, v120
	s_nop 0
	v_readfirstlane_b32 s74, v0
	s_mov_b32 m0, s74
	s_nop 0
	global_load_lds_dwordx4 v[24:25], off
	v_lshl_add_u64 v[24:25], v[98:99], 0, s[42:43]
	s_mov_b32 m0, s63
	v_mfma_f32_32x32x16_bf16 v[0:15], v[214:217], v[198:201], 0
	global_load_lds_dwordx4 v[24:25], off
	v_mfma_f32_32x32x16_bf16 v[16:31], v[218:221], v[198:201], 0
	v_bitop3_b32 v105, v102, v122, 2 bitop3:0x36
	v_lshlrev_b32_e32 v110, 4, v105
	v_add_u32_e32 v105, v124, v110
	ds_read_b128 v[222:225], v105
	v_add_u32_e32 v126, v123, v110
	ds_read_b128 v[232:235], v126
	ds_read_b128 v[236:239], v105 offset:4096
	ds_read_b128 v[240:243], v105 offset:8192
	ds_read_b128 v[244:247], v105 offset:12288
	ds_read_b128 v[248:251], v105 offset:16384
	ds_read_b128 v[142:145], v105 offset:20480
	v_add_u32_e32 v127, 0xc000, v120
	s_mov_b64 s[86:87], 0x10080
	v_readfirstlane_b32 s78, v127
	v_lshl_add_u64 v[118:119], v[96:97], 0, s[86:87]
	s_mov_b32 m0, s78
	s_waitcnt lgkmcnt(5)
	v_mfma_f32_32x32x16_bf16 v[80:95], v[222:225], v[232:235], v[80:95]
	s_waitcnt lgkmcnt(3)
	v_mfma_f32_32x32x16_bf16 v[64:79], v[236:239], v[232:235], v[64:79]
	v_mfma_f32_32x32x16_bf16 v[48:63], v[240:243], v[232:235], v[48:63]
	s_waitcnt lgkmcnt(1)
	v_mfma_f32_32x32x16_bf16 v[0:15], v[248:251], v[232:235], v[0:15]
	v_add_u32_e32 v116, 0xc000, v121
	v_lshl_add_u64 v[114:115], v[98:99], 0, s[86:87]
	v_readfirstlane_b32 s64, v116
	v_mfma_f32_32x32x16_bf16 v[32:47], v[244:247], v[232:235], v[32:47]
	global_load_lds_dwordx4 v[118:119], off
	s_mov_b32 m0, s64
	s_nop 0
	global_load_lds_dwordx4 v[114:115], off
	s_waitcnt lgkmcnt(0)
	v_mfma_f32_32x32x16_bf16 v[16:31], v[142:145], v[232:235], v[16:31]
	v_bitop3_b32 v106, v102, v122, 4 bitop3:0x36
	v_lshlrev_b32_e32 v110, 4, v106
	v_add_u32_e32 v118, v124, v110
	ds_read_b128 v[146:149], v118
	v_add_u32_e32 v119, v123, v110
	ds_read_b128 v[150:153], v119
	ds_read_b128 v[194:197], v118 offset:4096
	ds_read_b128 v[198:201], v118 offset:8192
	ds_read_b128 v[202:205], v118 offset:12288
	ds_read_b128 v[206:209], v118 offset:16384
	ds_read_b128 v[210:213], v118 offset:20480
	s_mov_b64 s[86:87], 0x18080
	s_waitcnt lgkmcnt(5)
	v_mfma_f32_32x32x16_bf16 v[80:95], v[146:149], v[150:153], v[80:95]
	s_waitcnt lgkmcnt(3)
; #define SBAR() __builtin_amdgcn_sched_barrier(0)
; DEV void glds16(const u16* g, char* l) { __builtin_amdgcn_global_load_lds((const unsigned*)g, (unsigned*)l, 16, 0, 0); }
; template <int WM, int WN, int BN, int EPI>
; DEV void gemm_tile(const u16* __restrict__ A, int lda, const u16* __restrict__ Bt, int ldb, int K, int m0, char* lds,
;                    const Params& P, int layer, int batch, int nt) {
;     ...
;   for (int kt = 0; kt < nk; ++kt) {
;     const bool more = kt + 1 < nk;
;     const int nb = (kt + 1) & 1;
;     const char* as = As + (kt & 1) * 32768; const char* bs = Bs + (kt & 1) * 32768;
; #pragma unroll
;     for (int ks = 0; ks < 4; ++ks) {
;       if (more) { glds16(Ap + (long)ks * 64 * lda + (kt + 1) * 64, As + nb * 32768 + soff + ks * 8192);
;                   if (ks < NB) glds16(Bp + (long)ks * 64 * ldb + (kt + 1) * 64, Bs + nb * 32768 + soff + ks * 8192); }
;       SBAR();
;       bf16x8 xf[MI], wf[NI];
; #pragma unroll
;       for (int mi = 0; mi < MI; ++mi) xf[mi] = *reinterpret_cast<const bf16x8*>(as + swz128(wm * (MI * 32) + mi * 32 + r32, ks * 2 + hi));
; #pragma unroll
;       for (int ni = 0; ni < NI; ++ni) wf[ni] = *reinterpret_cast<const bf16x8*>(bs + swz128(wn * (NI * 32) + ni * 32 + r32, ks * 2 + hi));
; #pragma unroll
;       for (int mi = 0; mi < MI; ++mi)
; #pragma unroll
;         for (int ni = 0; ni < NI; ++ni) acc[mi][ni] = __builtin_amdgcn_mfma_f32_32x32x16_bf16(wf[ni], xf[mi], acc[mi][ni], 0, 0, 0);
;     }
;     asm volatile("s_waitcnt vmcnt(0)" ::: "memory");
;     __syncthreads();
	v_mfma_f32_32x32x16_bf16 v[64:79], v[194:197], v[150:153], v[64:79]
	v_mfma_f32_32x32x16_bf16 v[48:63], v[198:201], v[150:153], v[48:63]
	s_waitcnt lgkmcnt(1)
	v_mfma_f32_32x32x16_bf16 v[0:15], v[206:209], v[150:153], v[0:15]
	v_add_u32_e32 v116, 0xe000, v120
	v_lshl_add_u64 v[114:115], v[96:97], 0, s[86:87]
	v_readfirstlane_b32 s80, v116
	s_mov_b32 m0, s80
	v_mfma_f32_32x32x16_bf16 v[32:47], v[202:205], v[150:153], v[32:47]
	global_load_lds_dwordx4 v[114:115], off
	s_waitcnt lgkmcnt(0)
	v_mfma_f32_32x32x16_bf16 v[16:31], v[210:213], v[150:153], v[16:31]
	v_bitop3_b32 v106, v102, v122, 6 bitop3:0x36
	v_lshlrev_b32_e32 v110, 4, v106
	v_add_u32_e32 v124, v124, v110
	ds_read_b128 v[214:217], v124
	v_add_u32_e32 v120, v123, v110
	ds_read_b128 v[218:221], v120
	ds_read_b128 v[222:225], v124 offset:4096
	ds_read_b128 v[232:235], v124 offset:8192
	ds_read_b128 v[236:239], v124 offset:12288
	ds_read_b128 v[240:243], v124 offset:16384
	ds_read_b128 v[244:247], v124 offset:20480
	s_mov_b32 m0, s82
	s_mov_b64 s[82:83], 0x100
	s_waitcnt lgkmcnt(5)
	v_mfma_f32_32x32x16_bf16 v[80:95], v[214:217], v[218:221], v[80:95]
	s_waitcnt lgkmcnt(3)
	v_mfma_f32_32x32x16_bf16 v[64:79], v[222:225], v[218:221], v[64:79]
	v_mfma_f32_32x32x16_bf16 v[48:63], v[232:235], v[218:221], v[48:63]
	s_waitcnt lgkmcnt(1)
	v_mfma_f32_32x32x16_bf16 v[0:15], v[240:243], v[218:221], v[0:15]
	v_lshl_add_u64 v[116:117], v[96:97], 0, s[82:83]
	v_lshl_add_u64 v[114:115], v[98:99], 0, s[82:83]
	v_mfma_f32_32x32x16_bf16 v[32:47], v[236:239], v[218:221], v[32:47]
	s_waitcnt vmcnt(0)
	s_waitcnt vmcnt(0) lgkmcnt(0)
	s_barrier
	global_load_lds_dwordx4 v[116:117], off
	s_mov_b32 m0, s81
	v_mfma_f32_32x32x16_bf16 v[16:31], v[244:247], v[218:221], v[16:31]
	global_load_lds_dwordx4 v[114:115], off
	ds_read_b128 v[248:251], v104 offset:32768
	ds_read_b128 v[142:145], v125 offset:32768
	ds_read_b128 v[146:149], v104 offset:36864
	ds_read_b128 v[150:153], v104 offset:40960
	ds_read_b128 v[194:197], v104 offset:45056
	ds_read_b128 v[198:201], v104 offset:49152
	ds_read_b128 v[202:205], v104 offset:53248
	ds_read_b128 v[206:209], v105 offset:32768
	ds_read_b128 v[210:213], v126 offset:32768
	ds_read_b128 v[214:217], v105 offset:36864
	s_mov_b64 s[82:83], 0x8100
	s_mov_b32 m0, s79
	s_waitcnt lgkmcnt(8)
	v_mfma_f32_32x32x16_bf16 v[80:95], v[248:251], v[142:145], v[80:95]
	ds_read_b128 v[218:221], v105 offset:40960
	ds_read_b128 v[222:225], v105 offset:45056
	s_waitcnt lgkmcnt(8)
	v_mfma_f32_32x32x16_bf16 v[64:79], v[146:149], v[142:145], v[64:79]
	v_mfma_f32_32x32x16_bf16 v[48:63], v[150:153], v[142:145], v[48:63]
	ds_read_b128 v[232:235], v105 offset:49152
	ds_read_b128 v[236:239], v105 offset:53248
	s_waitcnt lgkmcnt(8)
	v_mfma_f32_32x32x16_bf16 v[0:15], v[198:201], v[142:145], v[0:15]
	v_lshl_add_u64 v[114:115], v[96:97], 0, s[82:83]
	v_mfma_f32_32x32x16_bf16 v[32:47], v[194:197], v[142:145], v[32:47]
	ds_read_b128 v[240:243], v118 offset:32768
	global_load_lds_dwordx4 v[114:115], off
	v_lshl_add_u64 v[114:115], v[98:99], 0, s[82:83]
	s_mov_b32 m0, s75
	s_nop 0
	global_load_lds_dwordx4 v[114:115], off
	s_waitcnt lgkmcnt(8)
	v_mfma_f32_32x32x16_bf16 v[16:31], v[202:205], v[142:145], v[16:31]
	ds_read_b128 v[244:247], v119 offset:32768
	ds_read_b128 v[248:251], v118 offset:36864
	s_mov_b64 s[82:83], 0x10100
	s_mov_b32 m0, s65
	s_waitcnt lgkmcnt(8)
	v_mfma_f32_32x32x16_bf16 v[80:95], v[206:209], v[210:213], v[80:95]
	ds_read_b128 v[142:145], v118 offset:40960
	ds_read_b128 v[146:149], v118 offset:45056
	s_waitcnt lgkmcnt(8)
	v_mfma_f32_32x32x16_bf16 v[64:79], v[214:217], v[210:213], v[64:79]
	v_mfma_f32_32x32x16_bf16 v[48:63], v[218:221], v[210:213], v[48:63]
	ds_read_b128 v[150:153], v118 offset:49152
	ds_read_b128 v[194:197], v118 offset:53248
	s_waitcnt lgkmcnt(8)
	v_mfma_f32_32x32x16_bf16 v[0:15], v[232:235], v[210:213], v[0:15]
	v_lshl_add_u64 v[114:115], v[96:97], 0, s[82:83]
	v_mfma_f32_32x32x16_bf16 v[32:47], v[222:225], v[210:213], v[32:47]
	ds_read_b128 v[198:201], v124 offset:32768
	global_load_lds_dwordx4 v[114:115], off
	v_lshl_add_u64 v[114:115], v[98:99], 0, s[82:83]
	s_mov_b32 m0, s61
	s_nop 0
	global_load_lds_dwordx4 v[114:115], off
	s_waitcnt lgkmcnt(8)
	v_mfma_f32_32x32x16_bf16 v[16:31], v[236:239], v[210:213], v[16:31]
	ds_read_b128 v[202:205], v120 offset:32768
	ds_read_b128 v[206:209], v124 offset:36864
	s_mov_b32 m0, s60
	s_mov_b64 s[60:61], 0x18100
	s_waitcnt lgkmcnt(8)
	v_mfma_f32_32x32x16_bf16 v[80:95], v[240:243], v[244:247], v[80:95]
	ds_read_b128 v[210:213], v124 offset:40960
	ds_read_b128 v[214:217], v124 offset:45056
	s_waitcnt lgkmcnt(8)
	v_mfma_f32_32x32x16_bf16 v[64:79], v[248:251], v[244:247], v[64:79]
	v_mfma_f32_32x32x16_bf16 v[48:63], v[142:145], v[244:247], v[48:63]
	ds_read_b128 v[218:221], v124 offset:49152
	ds_read_b128 v[222:225], v124 offset:53248
	s_waitcnt lgkmcnt(8)
	v_mfma_f32_32x32x16_bf16 v[0:15], v[150:153], v[244:247], v[0:15]
	v_lshl_add_u64 v[114:115], v[96:97], 0, s[60:61]
	v_mfma_f32_32x32x16_bf16 v[32:47], v[146:149], v[244:247], v[32:47]
	global_load_lds_dwordx4 v[114:115], off
	s_waitcnt lgkmcnt(7)
	v_mfma_f32_32x32x16_bf16 v[16:31], v[194:197], v[244:247], v[16:31]
	s_mov_b64 s[60:61], 0x180
	s_mov_b32 m0, s62
	s_waitcnt lgkmcnt(5)
	v_mfma_f32_32x32x16_bf16 v[80:95], v[198:201], v[202:205], v[80:95]
	s_waitcnt lgkmcnt(3)
	v_mfma_f32_32x32x16_bf16 v[64:79], v[206:209], v[202:205], v[64:79]
	v_mfma_f32_32x32x16_bf16 v[48:63], v[210:213], v[202:205], v[48:63]
	s_waitcnt lgkmcnt(1)
	v_mfma_f32_32x32x16_bf16 v[0:15], v[218:221], v[202:205], v[0:15]
	v_lshl_add_u64 v[116:117], v[96:97], 0, s[60:61]
	v_lshl_add_u64 v[114:115], v[98:99], 0, s[60:61]
	v_mfma_f32_32x32x16_bf16 v[32:47], v[214:217], v[202:205], v[32:47]
	s_waitcnt vmcnt(0)
	s_waitcnt vmcnt(0) lgkmcnt(0)
	s_barrier
; #define SBAR() __builtin_amdgcn_sched_barrier(0)
; DEV void glds16(const u16* g, char* l) { __builtin_amdgcn_global_load_lds((const unsigned*)g, (unsigned*)l, 16, 0, 0); }
; template <int WM, int WN, int BN, int EPI>
; DEV void gemm_tile(const u16* __restrict__ A, int lda, const u16* __restrict__ Bt, int ldb, int K, int m0, char* lds,
;                    const Params& P, int layer, int batch, int nt) {
;     ...
;   for (int kt = 0; kt < nk; ++kt) {
;     const bool more = kt + 1 < nk;
;     const int nb = (kt + 1) & 1;
;     const char* as = As + (kt & 1) * 32768; const char* bs = Bs + (kt & 1) * 32768;
; #pragma unroll
;     for (int ks = 0; ks < 4; ++ks) {
;       if (more) { glds16(Ap + (long)ks * 64 * lda + (kt + 1) * 64, As + nb * 32768 + soff + ks * 8192);
;                   if (ks < NB) glds16(Bp + (long)ks * 64 * ldb + (kt + 1) * 64, Bs + nb * 32768 + soff + ks * 8192); }
;       SBAR();
;       bf16x8 xf[MI], wf[NI];
; #pragma unroll
;       for (int mi = 0; mi < MI; ++mi) xf[mi] = *reinterpret_cast<const bf16x8*>(as + swz128(wm * (MI * 32) + mi * 32 + r32, ks * 2 + hi));
; #pragma unroll
;       for (int ni = 0; ni < NI; ++ni) wf[ni] = *reinterpret_cast<const bf16x8*>(bs + swz128(wn * (NI * 32) + ni * 32 + r32, ks * 2 + hi));
; #pragma unroll
;       for (int mi = 0; mi < MI; ++mi)
; #pragma unroll
;         for (int ni = 0; ni < NI; ++ni) acc[mi][ni] = __builtin_amdgcn_mfma_f32_32x32x16_bf16(wf[ni], xf[mi], acc[mi][ni], 0, 0, 0);
;     }
;     asm volatile("s_waitcnt vmcnt(0)" ::: "memory");
;     __syncthreads();
	global_load_lds_dwordx4 v[116:117], off
	s_mov_b32 m0, s22
	v_mfma_f32_32x32x16_bf16 v[16:31], v[222:225], v[202:205], v[16:31]
	global_load_lds_dwordx4 v[114:115], off
	ds_read_b128 v[232:235], v104
	ds_read_b128 v[236:239], v125
	ds_read_b128 v[240:243], v104 offset:4096
	ds_read_b128 v[244:247], v104 offset:8192
	ds_read_b128 v[248:251], v104 offset:12288
	ds_read_b128 v[142:145], v104 offset:16384
	ds_read_b128 v[146:149], v104 offset:20480
	ds_read_b128 v[150:153], v105
	ds_read_b128 v[194:197], v126
	ds_read_b128 v[198:201], v105 offset:4096
	s_mov_b64 s[60:61], 0x8180
	s_mov_b32 m0, s74
	s_waitcnt lgkmcnt(8)
	v_mfma_f32_32x32x16_bf16 v[80:95], v[232:235], v[236:239], v[80:95]
	ds_read_b128 v[202:205], v105 offset:8192
	ds_read_b128 v[206:209], v105 offset:12288
	s_waitcnt lgkmcnt(8)
	v_mfma_f32_32x32x16_bf16 v[64:79], v[240:243], v[236:239], v[64:79]
	v_mfma_f32_32x32x16_bf16 v[48:63], v[244:247], v[236:239], v[48:63]
	ds_read_b128 v[210:213], v105 offset:16384
	ds_read_b128 v[214:217], v105 offset:20480
	s_waitcnt lgkmcnt(8)
	v_mfma_f32_32x32x16_bf16 v[0:15], v[142:145], v[236:239], v[0:15]
	v_lshl_add_u64 v[114:115], v[96:97], 0, s[60:61]
	v_mfma_f32_32x32x16_bf16 v[32:47], v[248:251], v[236:239], v[32:47]
	ds_read_b128 v[218:221], v118
	global_load_lds_dwordx4 v[114:115], off
	v_lshl_add_u64 v[114:115], v[98:99], 0, s[60:61]
	s_mov_b32 m0, s63
	s_nop 0
	global_load_lds_dwordx4 v[114:115], off
	s_waitcnt lgkmcnt(8)
	v_mfma_f32_32x32x16_bf16 v[16:31], v[146:149], v[236:239], v[16:31]
	ds_read_b128 v[222:225], v119
	ds_read_b128 v[232:235], v118 offset:4096
	s_mov_b64 s[60:61], 0x10180
	s_mov_b32 m0, s78
	v_lshl_add_u64 v[98:99], v[98:99], 0, s[60:61]
	s_waitcnt lgkmcnt(8)
	v_mfma_f32_32x32x16_bf16 v[80:95], v[150:153], v[194:197], v[80:95]
	ds_read_b128 v[236:239], v118 offset:8192
	ds_read_b128 v[240:243], v118 offset:12288
	s_waitcnt lgkmcnt(8)
	v_mfma_f32_32x32x16_bf16 v[64:79], v[198:201], v[194:197], v[64:79]
	v_mfma_f32_32x32x16_bf16 v[48:63], v[202:205], v[194:197], v[48:63]
	ds_read_b128 v[244:247], v118 offset:16384
	ds_read_b128 v[248:251], v118 offset:20480
	s_waitcnt lgkmcnt(8)
	v_mfma_f32_32x32x16_bf16 v[0:15], v[210:213], v[194:197], v[0:15]
	v_lshl_add_u64 v[114:115], v[96:97], 0, s[60:61]
	v_mfma_f32_32x32x16_bf16 v[32:47], v[206:209], v[194:197], v[32:47]
	ds_read_b128 v[142:145], v124
	global_load_lds_dwordx4 v[114:115], off
	s_mov_b32 m0, s64
	s_nop 0
	global_load_lds_dwordx4 v[98:99], off
	s_waitcnt lgkmcnt(8)
	v_mfma_f32_32x32x16_bf16 v[16:31], v[214:217], v[194:197], v[16:31]
	ds_read_b128 v[146:149], v120
	ds_read_b128 v[150:153], v124 offset:4096
	s_mov_b64 s[60:61], 0x18180
	s_mov_b32 m0, s80
	v_lshl_add_u64 v[96:97], v[96:97], 0, s[60:61]
	s_waitcnt lgkmcnt(8)
	v_mfma_f32_32x32x16_bf16 v[80:95], v[218:221], v[222:225], v[80:95]
	ds_read_b128 v[194:197], v124 offset:8192
	ds_read_b128 v[198:201], v124 offset:12288
	s_waitcnt lgkmcnt(8)
	v_mfma_f32_32x32x16_bf16 v[64:79], v[232:235], v[222:225], v[64:79]
	v_mfma_f32_32x32x16_bf16 v[48:63], v[236:239], v[222:225], v[48:63]
	ds_read_b128 v[202:205], v124 offset:16384
	ds_read_b128 v[206:209], v124 offset:20480
	s_waitcnt lgkmcnt(8)
	v_mfma_f32_32x32x16_bf16 v[32:47], v[240:243], v[222:225], v[32:47]
	global_load_lds_dwordx4 v[96:97], off
	v_mfma_f32_32x32x16_bf16 v[0:15], v[244:247], v[222:225], v[0:15]
	s_waitcnt lgkmcnt(7)
	v_mfma_f32_32x32x16_bf16 v[16:31], v[248:251], v[222:225], v[16:31]
	s_waitcnt lgkmcnt(5)
	v_mfma_f32_32x32x16_bf16 v[80:95], v[142:145], v[146:149], v[80:95]
	s_waitcnt lgkmcnt(4)
	v_mfma_f32_32x32x16_bf16 v[64:79], v[150:153], v[146:149], v[64:79]
	s_waitcnt lgkmcnt(3)
	v_mfma_f32_32x32x16_bf16 v[48:63], v[194:197], v[146:149], v[48:63]
	s_waitcnt lgkmcnt(2)
	v_mfma_f32_32x32x16_bf16 v[32:47], v[198:201], v[146:149], v[32:47]
	s_waitcnt lgkmcnt(1)
	v_mfma_f32_32x32x16_bf16 v[0:15], v[202:205], v[146:149], v[0:15]
	s_waitcnt vmcnt(0)
	s_waitcnt vmcnt(0) lgkmcnt(0)
	s_barrier
	v_mfma_f32_32x32x16_bf16 v[16:31], v[206:209], v[146:149], v[16:31]
	ds_read_b128 v[210:213], v104 offset:32768
	ds_read_b128 v[214:217], v125 offset:32768
	ds_read_b128 v[218:221], v104 offset:36864
	ds_read_b128 v[222:225], v104 offset:40960
	ds_read_b128 v[232:235], v104 offset:45056
	ds_read_b128 v[236:239], v104 offset:49152
	ds_read_b128 v[240:243], v104 offset:53248
	ds_read_b128 v[244:247], v105 offset:32768
	ds_read_b128 v[248:251], v126 offset:32768
	ds_read_b128 v[142:145], v105 offset:36864
	s_waitcnt lgkmcnt(8)
	v_mfma_f32_32x32x16_bf16 v[80:95], v[210:213], v[214:217], v[80:95]
	ds_read_b128 v[146:149], v105 offset:40960
	s_waitcnt lgkmcnt(8)
	v_mfma_f32_32x32x16_bf16 v[64:79], v[218:221], v[214:217], v[64:79]
	ds_read_b128 v[150:153], v105 offset:45056
	s_waitcnt lgkmcnt(8)
	v_mfma_f32_32x32x16_bf16 v[48:63], v[222:225], v[214:217], v[48:63]
	ds_read_b128 v[194:197], v105 offset:49152
	s_waitcnt lgkmcnt(8)
	v_mfma_f32_32x32x16_bf16 v[32:47], v[232:235], v[214:217], v[32:47]
	ds_read_b128 v[198:201], v105 offset:53248
	s_waitcnt lgkmcnt(8)
	v_mfma_f32_32x32x16_bf16 v[0:15], v[236:239], v[214:217], v[0:15]
	ds_read_b128 v[202:205], v118 offset:32768
	s_waitcnt lgkmcnt(8)
	v_mfma_f32_32x32x16_bf16 v[16:31], v[240:243], v[214:217], v[16:31]
	ds_read_b128 v[206:209], v119 offset:32768
	ds_read_b128 v[210:213], v118 offset:36864
	s_waitcnt lgkmcnt(8)
	v_mfma_f32_32x32x16_bf16 v[80:95], v[244:247], v[248:251], v[80:95]
	ds_read_b128 v[214:217], v118 offset:40960
	s_waitcnt lgkmcnt(8)
	v_mfma_f32_32x32x16_bf16 v[64:79], v[142:145], v[248:251], v[64:79]
	ds_read_b128 v[218:221], v118 offset:45056
	s_waitcnt lgkmcnt(8)
; #define SBAR() __builtin_amdgcn_sched_barrier(0)
; DEV void glds16(const u16* g, char* l) { __builtin_amdgcn_global_load_lds((const unsigned*)g, (unsigned*)l, 16, 0, 0); }
; DEV void epi_uq(f32x16 (&acc)[1][6], const Params& P, int layer, int batch, int m0, int head, int wid, int r32, int hi, char* lds) {
;   const int t = m0 + wid * 32 + r32;
;   const float rc = __builtin_amdgcn_rsqf((WS{P.ws}.ssq_cq()[t] + WS{P.ws}.ssq_cq()[TB + t] + WS{P.ws}.ssq_cq()[2 * TB + t] + WS{P.ws}.ssq_cq()[3 * TB + t]) * (1.f / 256.f) + EPS);
;   float s = 0.f;
; #pragma unroll
;   for (int ni = 0; ni < 6; ++ni)
; #pragma unroll
;     for (int r = 0; r < 16; ++r) { acc[0][ni][r] *= rc; s += acc[0][ni][r] * acc[0][ni][r]; }
; template <int WM, int WN, int BN, int EPI>
; DEV void gemm_tile(const u16* __restrict__ A, int lda, const u16* __restrict__ Bt, int ldb, int K, int m0, char* lds,
;                    const Params& P, int layer, int batch, int nt) {
;     ...
; #pragma unroll
;     for (int ks = 0; ks < 4; ++ks) {
;       if (more) { glds16(Ap + (long)ks * 64 * lda + (kt + 1) * 64, As + nb * 32768 + soff + ks * 8192);
;                   if (ks < NB) glds16(Bp + (long)ks * 64 * ldb + (kt + 1) * 64, Bs + nb * 32768 + soff + ks * 8192); }
;       SBAR();
;       bf16x8 xf[MI], wf[NI];
; #pragma unroll
;       for (int mi = 0; mi < MI; ++mi) xf[mi] = *reinterpret_cast<const bf16x8*>(as + swz128(wm * (MI * 32) + mi * 32 + r32, ks * 2 + hi));
; #pragma unroll
;       for (int ni = 0; ni < NI; ++ni) wf[ni] = *reinterpret_cast<const bf16x8*>(bs + swz128(wn * (NI * 32) + ni * 32 + r32, ks * 2 + hi));
; #pragma unroll
;       for (int mi = 0; mi < MI; ++mi)
; #pragma unroll
;         for (int ni = 0; ni < NI; ++ni) acc[mi][ni] = __builtin_amdgcn_mfma_f32_32x32x16_bf16(wf[ni], xf[mi], acc[mi][ni], 0, 0, 0);
;     }
;     asm volatile("s_waitcnt vmcnt(0)" ::: "memory");
;     __syncthreads();
	v_mfma_f32_32x32x16_bf16 v[48:63], v[146:149], v[248:251], v[48:63]
	ds_read_b128 v[222:225], v118 offset:49152
	s_waitcnt lgkmcnt(8)
	v_mfma_f32_32x32x16_bf16 v[32:47], v[150:153], v[248:251], v[32:47]
	ds_read_b128 v[232:235], v118 offset:53248
	s_waitcnt lgkmcnt(8)
	v_mfma_f32_32x32x16_bf16 v[0:15], v[194:197], v[248:251], v[0:15]
	s_waitcnt lgkmcnt(7)
	v_mfma_f32_32x32x16_bf16 v[16:31], v[198:201], v[248:251], v[16:31]
	s_waitcnt lgkmcnt(5)
	v_mfma_f32_32x32x16_bf16 v[80:95], v[202:205], v[206:209], v[80:95]
	s_waitcnt lgkmcnt(4)
	v_mfma_f32_32x32x16_bf16 v[64:79], v[210:213], v[206:209], v[64:79]
	s_waitcnt lgkmcnt(3)
	v_mfma_f32_32x32x16_bf16 v[48:63], v[214:217], v[206:209], v[48:63]
	s_waitcnt lgkmcnt(2)
	v_mfma_f32_32x32x16_bf16 v[32:47], v[218:221], v[206:209], v[32:47]
	s_waitcnt lgkmcnt(1)
	v_mfma_f32_32x32x16_bf16 v[0:15], v[222:225], v[206:209], v[0:15]
	s_waitcnt lgkmcnt(0)
	v_mfma_f32_32x32x16_bf16 v[16:31], v[232:235], v[206:209], v[16:31]
	ds_read_b128 v[96:99], v124 offset:32768
	ds_read_b128 v[104:107], v120 offset:32768
	ds_read_b128 v[108:111], v124 offset:36864
	ds_read_b128 v[112:115], v124 offset:40960
	ds_read_b128 v[116:119], v124 offset:45056
	ds_read_b128 v[120:123], v124 offset:49152
	ds_read_b128 v[124:127], v124 offset:53248
	s_waitcnt vmcnt(0)
	s_waitcnt lgkmcnt(5)
	v_mfma_f32_32x32x16_bf16 v[80:95], v[96:99], v[104:107], v[80:95]
	v_lshl_add_u32 v99, v103, 5, s3
	v_or_b32_e32 v96, v99, v101
	v_ashrrev_i32_e32 v97, 31, v96
	s_mov_b32 s3, 0x20000
	s_waitcnt lgkmcnt(0)
	s_barrier
	v_mfma_f32_32x32x16_bf16 v[64:79], v[108:111], v[104:107], v[64:79]
	v_lshl_add_u64 v[108:109], v[96:97], 2, s[8:9]
	v_add_co_u32_e32 v110, vcc, s93, v108
	v_lshlrev_b32_e32 v184, 4, v102
	s_nop 0
	v_addc_co_u32_e32 v111, vcc, 0, v109, vcc
	s_lshl_b32 s22, s2, 1
	v_mfma_f32_32x32x16_bf16 v[48:63], v[112:115], v[104:107], v[48:63]
	v_add_co_u32_e32 v112, vcc, s3, v108
	s_mov_b32 s3, 0x30000
	s_nop 0
	v_addc_co_u32_e32 v113, vcc, 0, v109, vcc
	v_add_co_u32_e32 v114, vcc, s3, v108
	v_mfma_f32_32x32x16_bf16 v[32:47], v[116:119], v[104:107], v[32:47]
	s_nop 0
	v_addc_co_u32_e32 v115, vcc, 0, v109, vcc
	flat_load_dword v97, v[108:109]
	flat_load_dword v98, v[110:111]
	s_nop 0
	flat_load_dword v108, v[112:113]
	flat_load_dword v109, v[114:115]
	s_movk_i32 s3, 0xfff
	s_waitcnt vmcnt(0) lgkmcnt(0)
	v_add_f32_e32 v97, v97, v98
	v_add_f32_e32 v97, v97, v108
	v_add_f32_e32 v97, v97, v109
	v_fmamk_f32 v97, v97, 0x3b800000, v227
	v_rsq_f32_e32 v98, v97
	v_mfma_f32_32x32x16_bf16 v[0:15], v[120:123], v[104:107], v[0:15]
	v_mul_f32_e32 v108, v81, v98
	v_mul_f32_e32 v97, v80, v98
	v_mul_f32_e32 v113, v86, v98
	v_mul_f32_e32 v86, v108, v108
	v_mul_f32_e32 v109, v82, v98
	v_fmac_f32_e32 v86, v97, v97
	v_mul_f32_e32 v110, v83, v98
	v_fmac_f32_e32 v86, v109, v109
	v_mul_f32_e32 v111, v84, v98
	v_fmac_f32_e32 v86, v110, v110
	v_mul_f32_e32 v112, v85, v98
	v_fmac_f32_e32 v86, v111, v111
	v_fmac_f32_e32 v86, v112, v112
	v_mul_f32_e32 v114, v87, v98
	v_fmac_f32_e32 v86, v113, v113
	v_mul_f32_e32 v115, v88, v98
	v_fmac_f32_e32 v86, v114, v114
	v_mul_f32_e32 v116, v89, v98
	v_fmac_f32_e32 v86, v115, v115
	v_mul_f32_e32 v117, v90, v98
	v_fmac_f32_e32 v86, v116, v116
	v_mul_f32_e32 v118, v91, v98
	v_fmac_f32_e32 v86, v117, v117
	v_mul_f32_e32 v119, v92, v98
	v_fmac_f32_e32 v86, v118, v118
	v_mul_f32_e32 v120, v93, v98
	v_fmac_f32_e32 v86, v119, v119
	v_mul_f32_e32 v121, v94, v98
	v_fmac_f32_e32 v86, v120, v120
	v_mul_f32_e32 v122, v95, v98
	v_fmac_f32_e32 v86, v121, v121
	v_mul_f32_e32 v123, v64, v98
	v_fmac_f32_e32 v86, v122, v122
	v_mfma_f32_32x32x16_bf16 v[16:31], v[124:127], v[104:107], v[16:31]
	v_mul_f32_e32 v124, v65, v98
	v_fmac_f32_e32 v86, v123, v123
	v_mul_f32_e32 v125, v66, v98
	v_fmac_f32_e32 v86, v124, v124
	v_mul_f32_e32 v126, v67, v98
	v_fmac_f32_e32 v86, v125, v125
	v_mul_f32_e32 v127, v68, v98
	v_fmac_f32_e32 v86, v126, v126
	v_mul_f32_e32 v128, v69, v98
	v_fmac_f32_e32 v86, v127, v127
	v_mul_f32_e32 v129, v70, v98
	v_fmac_f32_e32 v86, v128, v128
	v_mul_f32_e32 v130, v71, v98
	v_fmac_f32_e32 v86, v129, v129
	v_mul_f32_e32 v80, v72, v98
	v_fmac_f32_e32 v86, v130, v130
	v_mul_f32_e32 v81, v73, v98
	v_fmac_f32_e32 v86, v80, v80
	v_mul_f32_e32 v82, v74, v98
	v_fmac_f32_e32 v86, v81, v81
	v_mul_f32_e32 v83, v75, v98
	v_fmac_f32_e32 v86, v82, v82
	v_mul_f32_e32 v72, v76, v98
	v_fmac_f32_e32 v86, v83, v83
	v_mul_f32_e32 v73, v77, v98
	v_fmac_f32_e32 v86, v72, v72
	v_mul_f32_e32 v74, v78, v98
	v_fmac_f32_e32 v86, v73, v73
	v_mul_f32_e32 v75, v79, v98
	v_fmac_f32_e32 v86, v74, v74
	v_mul_f32_e32 v131, v36, v98
	v_mul_f32_e32 v132, v37, v98
	v_lshl_add_u64 v[36:37], s[10:11], 0, v[184:185]
	v_mul_f32_e32 v68, v48, v98
	v_mul_f32_e32 v70, v50, v98
	v_mul_f32_e32 v71, v51, v98
	v_mul_f32_e32 v66, v54, v98
	v_mul_f32_e32 v67, v55, v98
	v_mul_f32_e32 v54, v56, v98
	v_mul_f32_e32 v55, v57, v98
	v_mul_f32_e32 v56, v58, v98
	v_mul_f32_e32 v57, v59, v98
	v_mul_f32_e32 v50, v60, v98
	v_mul_f32_e32 v51, v61, v98
	v_fmac_f32_e32 v86, v75, v75
	flat_load_dwordx4 v[58:61], v[36:37] offset:1280
	global_load_dwordx4 v[194:197], v[36:37], off offset:1312
	global_load_dwordx4 v[198:201], v[36:37], off offset:1344
	global_load_dwordx4 v[202:205], v[36:37], off offset:1376
	global_load_dwordx4 v[206:209], v[36:37], off offset:1408
	global_load_dwordx4 v[210:213], v[36:37], off offset:1440
	global_load_dwordx4 v[214:217], v[36:37], off offset:1472
	global_load_dwordx4 v[218:221], v[36:37], off offset:1504
	global_load_dwordx4 v[222:225], v[36:37], off offset:1536
	global_load_dwordx4 v[232:235], v[36:37], off offset:1568
	global_load_dwordx4 v[236:239], v[36:37], off offset:1600
; DEV void epi_uq(f32x16 (&acc)[1][6], const Params& P, int layer, int batch, int m0, int head, int wid, int r32, int hi, char* lds) {
;   const int t = m0 + wid * 32 + r32;
;   const float rc = __builtin_amdgcn_rsqf((WS{P.ws}.ssq_cq()[t] + WS{P.ws}.ssq_cq()[TB + t] + WS{P.ws}.ssq_cq()[2 * TB + t] + WS{P.ws}.ssq_cq()[3 * TB + t]) * (1.f / 256.f) + EPS);
;   float s = 0.f;
; #pragma unroll
;   for (int ni = 0; ni < 6; ++ni)
; #pragma unroll
;     for (int r = 0; r < 16; ++r) { acc[0][ni][r] *= rc; s += acc[0][ni][r] * acc[0][ni][r]; }
;   s = swapsum(s);
;   constexpr float SCQ = 0.07216878364870323f * LOG2E;
;   const float inv = __builtin_amdgcn_rsqf(s * (1.f / 192.f) + EPS) * SCQ;
;   const float* g = WS{P.ws}.consts() + layer * 1024 + 320;
;   char* slab = lds + wid * 12800; char* dst = slab + r32 * 400;
	global_load_dwordx4 v[240:243], v[36:37], off offset:1632
	global_load_dwordx4 v[244:247], v[36:37], off offset:1664
	global_load_dwordx4 v[248:251], v[36:37], off offset:1696
	global_load_dwordx4 v[170:173], v[36:37], off offset:1728
	global_load_dwordx4 v[174:177], v[36:37], off offset:1760
	v_mul_f32_e32 v69, v49, v98
	v_fmac_f32_e32 v86, v68, v68
	v_fmac_f32_e32 v86, v69, v69
	v_fmac_f32_e32 v86, v70, v70
	v_mul_f32_e32 v64, v52, v98
	v_fmac_f32_e32 v86, v71, v71
	v_mul_f32_e32 v65, v53, v98
	v_fmac_f32_e32 v86, v64, v64
	v_fmac_f32_e32 v86, v65, v65
	v_fmac_f32_e32 v86, v66, v66
	v_fmac_f32_e32 v86, v67, v67
	v_fmac_f32_e32 v86, v54, v54
	v_fmac_f32_e32 v86, v55, v55
	v_fmac_f32_e32 v86, v56, v56
	v_fmac_f32_e32 v86, v57, v57
	v_fmac_f32_e32 v86, v50, v50
	v_mul_f32_e32 v52, v62, v98
	v_fmac_f32_e32 v86, v51, v51
	v_mul_f32_e32 v53, v63, v98
	v_fmac_f32_e32 v86, v52, v52
	v_mul_f32_e32 v48, v32, v98
	v_fmac_f32_e32 v86, v53, v53
	v_mul_f32_e32 v33, v33, v98
	v_fmac_f32_e32 v86, v48, v48
	v_mul_f32_e32 v49, v34, v98
	v_fmac_f32_e32 v86, v33, v33
	v_mul_f32_e32 v35, v35, v98
	v_fmac_f32_e32 v86, v49, v49
	v_fmac_f32_e32 v86, v35, v35
	v_fmac_f32_e32 v86, v131, v131
	v_fmac_f32_e32 v86, v132, v132
	v_mul_f32_e32 v133, v38, v98
	v_fmac_f32_e32 v86, v133, v133
	v_mul_f32_e32 v134, v39, v98
	v_fmac_f32_e32 v86, v134, v134
	v_mul_f32_e32 v135, v40, v98
	v_fmac_f32_e32 v86, v135, v135
	v_mul_f32_e32 v136, v41, v98
	v_fmac_f32_e32 v86, v136, v136
	v_mul_f32_e32 v137, v42, v98
	v_fmac_f32_e32 v86, v137, v137
	v_mul_f32_e32 v138, v43, v98
	v_fmac_f32_e32 v86, v138, v138
	v_mul_f32_e32 v139, v44, v98
	v_fmac_f32_e32 v86, v139, v139
	v_mul_f32_e32 v140, v45, v98
	v_mul_f32_e32 v34, v14, v98
	v_mul_lo_u32 v14, v103, s99
	v_fmac_f32_e32 v86, v140, v140
	v_mul_f32_e32 v141, v46, v98
	v_mul_f32_e32 v32, v15, v98
	v_add_u32_e32 v46, 0, v14
	v_mov_b32_e32 v14, v2
	v_mov_b32_e32 v15, v18
	v_mov_b32_e32 v18, v3
	v_mov_b32_e32 v2, v0
	v_mov_b32_e32 v3, v16
	v_fmac_f32_e32 v86, v141, v141
	v_mul_f32_e32 v47, v47, v98
	v_pk_mul_f32 v[42:43], v[2:3], v[98:99] op_sel_hi:[1,0]
	v_mov_b32_e32 v16, v1
	v_fmac_f32_e32 v86, v47, v47
	v_pk_mul_f32 v[84:85], v[42:43], v[42:43]
	v_pk_mul_f32 v[44:45], v[16:17], v[98:99] op_sel_hi:[1,0]
	v_pk_mul_f32 v[14:15], v[14:15], v[98:99] op_sel_hi:[1,0]
	v_add_f32_e32 v0, v84, v86
	v_pk_mul_f32 v[86:87], v[44:45], v[44:45]
	v_pk_mul_f32 v[76:77], v[14:15], v[14:15]
	v_pk_mul_f32 v[40:41], v[18:19], v[98:99] op_sel_hi:[1,0]
	v_add_f32_e32 v0, v86, v0
	v_pk_mul_f32 v[78:79], v[40:41], v[40:41]
	v_add_f32_e32 v0, v76, v0
	v_add_f32_e32 v16, v78, v0
	v_mov_b32_e32 v0, v6
	v_mov_b32_e32 v1, v22
	v_mov_b32_e32 v22, v7
	v_mov_b32_e32 v6, v4
	v_mov_b32_e32 v7, v20
	v_pk_mul_f32 v[6:7], v[6:7], v[98:99] op_sel_hi:[1,0]
	v_mov_b32_e32 v20, v5
	v_pk_mul_f32 v[92:93], v[6:7], v[6:7]
	v_pk_mul_f32 v[4:5], v[20:21], v[98:99] op_sel_hi:[1,0]
	v_pk_mul_f32 v[0:1], v[0:1], v[98:99] op_sel_hi:[1,0]
	v_add_f32_e32 v16, v92, v16
	v_pk_mul_f32 v[20:21], v[4:5], v[4:5]
	v_pk_mul_f32 v[88:89], v[0:1], v[0:1]
	v_pk_mul_f32 v[2:3], v[22:23], v[98:99] op_sel_hi:[1,0]
	v_add_f32_e32 v16, v20, v16
	v_pk_mul_f32 v[90:91], v[2:3], v[2:3]
	v_add_f32_e32 v16, v88, v16
	v_add_f32_e32 v18, v90, v16
	v_mov_b32_e32 v16, v10
	v_mov_b32_e32 v17, v26
	v_pk_mul_f32 v[22:23], v[16:17], v[98:99] op_sel_hi:[1,0]
	v_mov_b32_e32 v16, v8
	v_mov_b32_e32 v17, v24
	v_pk_mul_f32 v[38:39], v[16:17], v[98:99] op_sel_hi:[1,0]
	v_mov_b32_e32 v24, v9
	v_pk_mul_f32 v[104:105], v[38:39], v[38:39]
	v_pk_mul_f32 v[24:25], v[24:25], v[98:99] op_sel_hi:[1,0]
	v_mov_b32_e32 v26, v11
	v_add_f32_e32 v16, v104, v18
	v_pk_mul_f32 v[8:9], v[24:25], v[24:25]
	v_pk_mul_f32 v[94:95], v[22:23], v[22:23]
	v_pk_mul_f32 v[26:27], v[26:27], v[98:99] op_sel_hi:[1,0]
	v_add_f32_e32 v8, v8, v16
	v_mov_b32_e32 v16, v12
	v_mov_b32_e32 v17, v28
	v_pk_mul_f32 v[10:11], v[26:27], v[26:27]
	v_add_f32_e32 v8, v94, v8
	v_pk_mul_f32 v[16:17], v[16:17], v[98:99] op_sel_hi:[1,0]
	v_mov_b32_e32 v28, v13
	v_add_f32_e32 v8, v10, v8
	v_pk_mul_f32 v[106:107], v[16:17], v[16:17]
	v_pk_mul_f32 v[18:19], v[28:29], v[98:99] op_sel_hi:[1,0]
	v_add_f32_e32 v8, v106, v8
	v_pk_mul_f32 v[12:13], v[18:19], v[18:19]
	v_pk_mul_f32 v[30:31], v[30:31], v[98:99] op_sel_hi:[1,0]
	v_add_f32_e32 v8, v12, v8
	v_fmac_f32_e32 v8, v34, v34
	v_fmac_f32_e32 v8, v32, v32
	v_add_f32_e32 v8, v85, v8
	v_add_f32_e32 v8, v87, v8
	v_add_f32_e32 v8, v77, v8
	v_add_f32_e32 v8, v79, v8
	v_add_f32_e32 v8, v93, v8
	v_add_f32_e32 v8, v21, v8
	v_add_f32_e32 v8, v89, v8
	v_add_f32_e32 v8, v91, v8
	v_add_f32_e32 v8, v105, v8
	v_add_f32_e32 v8, v9, v8
	v_add_f32_e32 v8, v95, v8
	v_add_f32_e32 v8, v11, v8
	v_add_f32_e32 v8, v107, v8
	v_pk_mul_f32 v[62:63], v[30:31], v[30:31]
	v_add_f32_e32 v8, v13, v8
	v_add_f32_e32 v8, v62, v8
	v_add_f32_e32 v8, v63, v8
	v_mov_b32_e32 v9, v8
	s_nop 1
	v_permlane32_swap_b32_e32 v8, v9
	v_add_f32_e32 v8, v8, v9
	v_fmamk_f32 v8, v8, 0x3baaaaab, v227
	v_rsq_f32_e32 v8, v8
	v_mul_u32_u24_e32 v9, 0x190, v101
	v_lshlrev_b32_e32 v10, 3, v102
	v_add3_u32 v21, v46, v9, v10
	v_mul_f32_e32 v20, 0x3dd53b94, v8
	v_mul_f32_e32 v8, v97, v20
	v_mul_f32_e32 v9, v108, v20
	s_waitcnt vmcnt(0) lgkmcnt(0)
; DEV void epi_uq(f32x16 (&acc)[1][6], const Params& P, int layer, int batch, int m0, int head, int wid, int r32, int hi, char* lds) {
;     ...
;   const float* g = WS{P.ws}.consts() + layer * 1024 + 320;
;   char* slab = lds + wid * 12800; char* dst = slab + r32 * 400;
; #pragma unroll
;   for (int ni = 0; ni < 4; ++ni)
; #pragma unroll
;     for (int r4 = 0; r4 < 4; ++r4) {
;       const int c = ni * 32 + r4 * 8 + hi * 4;
;       const float4 gg = *reinterpret_cast<const float4*>(g + c);
;       const f32x16& a = acc[0][ni];
;       st4lds(dst, c, a[r4 * 4] * inv * gg.x, a[r4 * 4 + 1] * inv * gg.y, a[r4 * 4 + 2] * inv * gg.z, a[r4 * 4 + 3] * inv * gg.w);
;     }
;   const int pos = batch ? t : (t & 4095);
;   const float2* rp = WS{P.ws}.rope() + (long)pos * 32;
; #pragma unroll
;   for (int r4 = 0; r4 < 4; ++r4) {
;     const int i = r4 * 8 + hi * 4;
;     const float4 g1 = *reinterpret_cast<const float4*>(g + 128 + i), g2 = *reinterpret_cast<const float4*>(g + 160 + i);
;     const float4 cs01 = *reinterpret_cast<const float4*>(rp + i), cs23 = *reinterpret_cast<const float4*>(rp + i + 2);
	v_mul_f32_e32 v8, v58, v8
	v_mul_f32_e32 v9, v59, v9
	v_mul_f32_e32 v10, v109, v20
	v_mul_f32_e32 v11, v110, v20
	v_mul_f32_e32 v10, v60, v10
	v_mul_f32_e32 v11, v61, v11
	v_cvt_pk_bf16_f32 v8, v8, v9
	v_cvt_pk_bf16_f32 v9, v10, v11
	ds_write_b64 v21, v[8:9]
	v_mul_f32_e32 v12, v111, v20
	v_mul_f32_e32 v13, v116, v20
	v_mul_f32_e32 v28, v117, v20
	v_mul_f32_e32 v29, v118, v20
	v_lshlrev_b32_e32 v184, 5, v102
	v_pk_mul_f32 v[14:15], v[14:15], v[20:21] op_sel_hi:[1,0]
	v_pk_mul_f32 v[40:41], v[40:41], v[20:21] op_sel_hi:[1,0]
	v_pk_mul_f32 v[6:7], v[6:7], v[20:21] op_sel_hi:[1,0]
	v_pk_mul_f32 v[4:5], v[4:5], v[20:21] op_sel_hi:[1,0]
	v_pk_mul_f32 v[0:1], v[0:1], v[20:21] op_sel_hi:[1,0]
	v_pk_mul_f32 v[2:3], v[2:3], v[20:21] op_sel_hi:[1,0]
	v_pk_mul_f32 v[38:39], v[38:39], v[20:21] op_sel_hi:[1,0]
	v_pk_mul_f32 v[24:25], v[24:25], v[20:21] op_sel_hi:[1,0]
	v_pk_mul_f32 v[22:23], v[22:23], v[20:21] op_sel_hi:[1,0]
	v_pk_mul_f32 v[26:27], v[26:27], v[20:21] op_sel_hi:[1,0]
	v_pk_mul_f32 v[16:17], v[16:17], v[20:21] op_sel_hi:[1,0]
	v_pk_mul_f32 v[18:19], v[18:19], v[20:21] op_sel_hi:[1,0]
	v_mul_f32_e32 v8, v194, v12
	v_mul_f32_e32 v12, v112, v20
	v_mul_f32_e32 v9, v12, v195
	v_mul_f32_e32 v12, v113, v20
	v_mul_f32_e32 v10, v12, v196
	v_mul_f32_e32 v12, v114, v20
	v_mul_f32_e32 v11, v12, v197
	v_cvt_pk_bf16_f32 v8, v8, v9
	v_cvt_pk_bf16_f32 v9, v10, v11
	ds_write_b64 v21, v[8:9] offset:16
	v_mul_f32_e32 v12, v115, v20
	v_mul_f32_e32 v8, v12, v198
	v_mul_f32_e32 v9, v13, v199
	v_mul_f32_e32 v10, v28, v200
	v_mul_f32_e32 v11, v29, v201
	v_cvt_pk_bf16_f32 v8, v8, v9
	v_cvt_pk_bf16_f32 v9, v10, v11
	ds_write_b64 v21, v[8:9] offset:32
	v_mul_f32_e32 v12, v119, v20
	v_mul_f32_e32 v13, v120, v20
	v_mul_f32_e32 v28, v121, v20
	v_mul_f32_e32 v29, v122, v20
	v_mul_f32_e32 v8, v12, v202
	v_mul_f32_e32 v9, v13, v203
	v_mul_f32_e32 v10, v28, v204
	v_mul_f32_e32 v11, v29, v205
	v_cvt_pk_bf16_f32 v8, v8, v9
	v_cvt_pk_bf16_f32 v9, v10, v11
	ds_write_b64 v21, v[8:9] offset:48
	v_mul_f32_e32 v12, v123, v20
	v_mul_f32_e32 v13, v124, v20
	v_mul_f32_e32 v28, v125, v20
	v_mul_f32_e32 v29, v126, v20
	v_mul_f32_e32 v8, v12, v206
	v_mul_f32_e32 v9, v13, v207
	v_mul_f32_e32 v10, v28, v208
	v_mul_f32_e32 v11, v29, v209
	v_cvt_pk_bf16_f32 v8, v8, v9
	v_cvt_pk_bf16_f32 v9, v10, v11
	ds_write_b64 v21, v[8:9] offset:64
	v_mul_f32_e32 v12, v127, v20
	v_mul_f32_e32 v13, v128, v20
	v_mul_f32_e32 v28, v129, v20
	v_mul_f32_e32 v29, v130, v20
	v_mul_f32_e32 v8, v12, v210
	v_mul_f32_e32 v9, v13, v211
	v_mul_f32_e32 v10, v28, v212
	v_mul_f32_e32 v11, v29, v213
	v_cvt_pk_bf16_f32 v8, v8, v9
	v_cvt_pk_bf16_f32 v9, v10, v11
	ds_write_b64 v21, v[8:9] offset:80
	v_mul_f32_e32 v12, v80, v20
	v_mul_f32_e32 v13, v81, v20
	v_mul_f32_e32 v28, v82, v20
	v_mul_f32_e32 v29, v83, v20
	v_mul_f32_e32 v8, v12, v214
	v_mul_f32_e32 v9, v13, v215
	v_mul_f32_e32 v10, v28, v216
	v_mul_f32_e32 v11, v29, v217
	v_cvt_pk_bf16_f32 v8, v8, v9
	v_cvt_pk_bf16_f32 v9, v10, v11
	ds_write_b64 v21, v[8:9] offset:96
	v_mul_f32_e32 v12, v72, v20
	v_mul_f32_e32 v13, v73, v20
	v_mul_f32_e32 v28, v74, v20
	v_mul_f32_e32 v29, v75, v20
	v_mul_f32_e32 v8, v12, v218
	v_mul_f32_e32 v9, v13, v219
	v_mul_f32_e32 v10, v28, v220
	v_mul_f32_e32 v11, v29, v221
	v_cvt_pk_bf16_f32 v8, v8, v9
	v_cvt_pk_bf16_f32 v9, v10, v11
	ds_write_b64 v21, v[8:9] offset:112
	v_mul_f32_e32 v12, v68, v20
	v_mul_f32_e32 v13, v69, v20
	v_mul_f32_e32 v28, v70, v20
	v_mul_f32_e32 v29, v71, v20
	v_mul_f32_e32 v8, v12, v222
	v_mul_f32_e32 v9, v13, v223
	v_mul_f32_e32 v10, v28, v224
	v_mul_f32_e32 v11, v29, v225
	v_cvt_pk_bf16_f32 v8, v8, v9
	v_cvt_pk_bf16_f32 v9, v10, v11
	ds_write_b64 v21, v[8:9] offset:128
	v_mul_f32_e32 v12, v64, v20
	v_mul_f32_e32 v13, v65, v20
	v_mul_f32_e32 v28, v66, v20
	v_mul_f32_e32 v29, v67, v20
	v_mul_f32_e32 v8, v12, v232
	v_mul_f32_e32 v9, v13, v233
	v_mul_f32_e32 v10, v28, v234
	v_mul_f32_e32 v11, v29, v235
	v_cvt_pk_bf16_f32 v8, v8, v9
	v_cvt_pk_bf16_f32 v9, v10, v11
	ds_write_b64 v21, v[8:9] offset:144
	v_mul_f32_e32 v12, v54, v20
	v_mul_f32_e32 v13, v55, v20
	v_mul_f32_e32 v28, v56, v20
	v_mul_f32_e32 v29, v57, v20
	v_mul_f32_e32 v8, v12, v236
	v_mul_f32_e32 v9, v13, v237
	v_mul_f32_e32 v10, v28, v238
	v_mul_f32_e32 v11, v29, v239
	v_cvt_pk_bf16_f32 v8, v8, v9
	v_cvt_pk_bf16_f32 v9, v10, v11
	ds_write_b64 v21, v[8:9] offset:160
	v_mul_f32_e32 v12, v50, v20
	v_mul_f32_e32 v13, v51, v20
	v_mul_f32_e32 v28, v52, v20
	v_mul_f32_e32 v29, v53, v20
	v_mul_f32_e32 v8, v12, v240
	v_mul_f32_e32 v9, v13, v241
	v_mul_f32_e32 v10, v28, v242
	v_mul_f32_e32 v11, v29, v243
	v_cvt_pk_bf16_f32 v8, v8, v9
	v_cvt_pk_bf16_f32 v9, v10, v11
	ds_write_b64 v21, v[8:9] offset:176
	v_mul_f32_e32 v12, v48, v20
	v_mul_f32_e32 v13, v33, v20
	v_mul_f32_e32 v28, v49, v20
	v_mul_f32_e32 v29, v35, v20
	v_mul_f32_e32 v8, v12, v244
	v_mul_f32_e32 v9, v13, v245
	v_mul_f32_e32 v10, v28, v246
	v_mul_f32_e32 v11, v29, v247
	v_cvt_pk_bf16_f32 v8, v8, v9
	v_cvt_pk_bf16_f32 v9, v10, v11
	ds_write_b64 v21, v[8:9] offset:192
	v_mul_f32_e32 v12, v131, v20
	v_mul_f32_e32 v13, v132, v20
	v_mul_f32_e32 v28, v133, v20
	v_mul_f32_e32 v29, v134, v20
	v_mul_f32_e32 v8, v12, v248
	v_mul_f32_e32 v9, v13, v249
	v_mul_f32_e32 v10, v28, v250
	v_mul_f32_e32 v11, v29, v251
	v_cvt_pk_bf16_f32 v8, v8, v9
	v_cvt_pk_bf16_f32 v9, v10, v11
	ds_write_b64 v21, v[8:9] offset:208
	v_mul_f32_e32 v12, v135, v20
	v_mul_f32_e32 v13, v136, v20
	v_mul_f32_e32 v28, v137, v20
	v_mul_f32_e32 v29, v138, v20
	v_mul_f32_e32 v8, v12, v170
	v_mul_f32_e32 v9, v13, v171
	v_mul_f32_e32 v10, v28, v172
	v_mul_f32_e32 v11, v29, v173
	v_cvt_pk_bf16_f32 v8, v8, v9
	v_cvt_pk_bf16_f32 v9, v10, v11
	ds_write_b64 v21, v[8:9] offset:224
	v_mul_f32_e32 v12, v139, v20
	v_mul_f32_e32 v13, v140, v20
	v_mul_f32_e32 v28, v141, v20
	v_mul_f32_e32 v29, v47, v20
	v_mul_f32_e32 v8, v12, v174
	v_bitop3_b32 v12, v99, s3, v101 bitop3:0xc8
	v_cndmask_b32_e64 v12, v96, v12, s[26:27]
	v_mul_f32_e32 v9, v13, v175
	v_ashrrev_i32_e32 v13, 31, v12
	v_mul_f32_e32 v10, v28, v176
	v_mul_f32_e32 v11, v29, v177
	v_cvt_pk_bf16_f32 v8, v8, v9
	v_cvt_pk_bf16_f32 v9, v10, v11
	ds_write_b64 v21, v[8:9] offset:240
	v_lshlrev_b64 v[12:13], 8, v[12:13]
	flat_load_dwordx4 v[8:11], v[36:37] offset:1792
	flat_load_dwordx4 v[48:51], v[36:37] offset:1920
	v_lshl_add_u64 v[12:13], s[12:13], 0, v[12:13]
	v_lshl_add_u64 v[28:29], v[12:13], 0, v[184:185]
	flat_load_dwordx4 v[52:55], v[28:29]
	flat_load_dwordx4 v[56:59], v[28:29] offset:16
	v_pk_mul_f32 v[12:13], v[42:43], v[20:21] op_sel_hi:[1,0]
	v_pk_mul_f32 v[42:43], v[44:45], v[20:21] op_sel_hi:[1,0]
	s_waitcnt vmcnt(0) lgkmcnt(0)
; DEV void epi_uq(f32x16 (&acc)[1][6], const Params& P, int layer, int batch, int m0, int head, int wid, int r32, int hi, char* lds) {
;     ...
;   const int pos = batch ? t : (t & 4095);
;   const float2* rp = WS{P.ws}.rope() + (long)pos * 32;
; #pragma unroll
;   for (int r4 = 0; r4 < 4; ++r4) {
;     const int i = r4 * 8 + hi * 4;
;     const float4 g1 = *reinterpret_cast<const float4*>(g + 128 + i), g2 = *reinterpret_cast<const float4*>(g + 160 + i);
;     const float4 cs01 = *reinterpret_cast<const float4*>(rp + i), cs23 = *reinterpret_cast<const float4*>(rp + i + 2);
;     const float x1[4] = {acc[0][4][r4 * 4] * inv * g1.x, acc[0][4][r4 * 4 + 1] * inv * g1.y, acc[0][4][r4 * 4 + 2] * inv * g1.z, acc[0][4][r4 * 4 + 3] * inv * g1.w};
;     const float x2[4] = {acc[0][5][r4 * 4] * inv * g2.x, acc[0][5][r4 * 4 + 1] * inv * g2.y, acc[0][5][r4 * 4 + 2] * inv * g2.z, acc[0][5][r4 * 4 + 3] * inv * g2.w};
;     const float cc[4] = {cs01.x, cs01.z, cs23.x, cs23.z}, sn[4] = {cs01.y, cs01.w, cs23.y, cs23.w};
;     st4lds(dst, 128 + i, x1[0] * cc[0] - x2[0] * sn[0], x1[1] * cc[1] - x2[1] * sn[1], x1[2] * cc[2] - x2[2] * sn[2], x1[3] * cc[3] - x2[3] * sn[3]);
;     st4lds(dst, 160 + i, x1[0] * sn[0] + x2[0] * cc[0], x1[1] * sn[1] + x2[1] * cc[1], x1[2] * sn[2] + x2[2] * cc[2], x1[3] * sn[3] + x2[3] * cc[3]);
;   }
;   slab_flush<24, 400>(slab, WS{P.ws}.QB() + (long)(m0 + wid * 32) * 768 + head * 192, 768, hi * 32 + r32);
	v_mov_b32_e32 v44, v8
	v_mov_b32_e32 v45, v48
	v_mov_b32_e32 v48, v9
	v_mov_b32_e32 v8, v10
	v_mov_b32_e32 v9, v50
	v_mov_b32_e32 v50, v11
	v_pk_mul_f32 v[10:11], v[12:13], v[44:45]
	v_pk_mul_f32 v[12:13], v[42:43], v[48:49]
	v_pk_mul_f32 v[8:9], v[14:15], v[8:9]
	v_pk_mul_f32 v[14:15], v[40:41], v[50:51]
	v_pk_mul_f32 v[40:41], v[10:11], v[52:53]
	v_pk_mul_f32 v[42:43], v[12:13], v[54:55]
	v_pk_mul_f32 v[44:45], v[8:9], v[56:57]
	v_pk_mul_f32 v[48:49], v[14:15], v[58:59]
	v_pk_mul_f32 v[10:11], v[10:11], v[52:53] op_sel:[1,0] op_sel_hi:[0,1]
	v_pk_mul_f32 v[12:13], v[12:13], v[54:55] op_sel:[1,0] op_sel_hi:[0,1]
	v_pk_mul_f32 v[8:9], v[8:9], v[56:57] op_sel:[1,0] op_sel_hi:[0,1]
	v_pk_mul_f32 v[14:15], v[14:15], v[58:59] op_sel:[1,0] op_sel_hi:[0,1]
	v_sub_f32_e32 v33, v40, v41
	v_sub_f32_e32 v35, v42, v43
	v_sub_f32_e32 v40, v44, v45
	v_sub_f32_e32 v41, v48, v49
	v_add_f32_e32 v10, v10, v11
	v_add_f32_e32 v11, v12, v13
	v_add_f32_e32 v12, v8, v9
	v_cvt_pk_bf16_f32 v8, v33, v35
	v_cvt_pk_bf16_f32 v9, v40, v41
	v_add_f32_e32 v13, v14, v15
	ds_write_b64 v21, v[8:9] offset:256
	v_cvt_pk_bf16_f32 v8, v10, v11
	v_cvt_pk_bf16_f32 v9, v12, v13
	ds_write_b64 v21, v[8:9] offset:320
	flat_load_dwordx4 v[8:11], v[36:37] offset:1824
	flat_load_dwordx4 v[12:15], v[36:37] offset:1952
	flat_load_dwordx4 v[40:43], v[28:29] offset:64
	flat_load_dwordx4 v[48:51], v[28:29] offset:80
	v_and_b32_e32 v33, 63, v100
	v_mul_lo_u16_e32 v35, 43, v33
	v_or_b32_e32 v47, 0xc0, v33
	v_or_b32_e32 v52, 0x1c0, v33
	v_or_b32_e32 v53, 0x280, v33
	v_or_b32_e32 v54, 0x240, v33
	v_or_b32_e32 v55, 0x2c0, v33
	v_lshrrev_b16_e32 v35, 10, v35
	v_mul_lo_u16_e32 v56, 0xab, v47
	v_mul_u32_u24_e32 v60, 0xaab, v52
	v_mul_u32_u24_e32 v62, 0xaab, v54
	v_mul_u32_u24_e32 v63, 0xaab, v53
	v_mul_u32_u24_e32 v64, 0xaab, v55
	v_lshrrev_b16_e32 v56, 12, v56
	v_mul_u32_u24_e32 v65, 0x190, v35
	v_lshrrev_b32_e32 v71, 16, v63
	s_waitcnt vmcnt(0) lgkmcnt(0)
	v_mov_b32_e32 v44, v8
	v_mov_b32_e32 v45, v12
	v_mov_b32_e32 v12, v9
	v_mov_b32_e32 v8, v10
	v_mov_b32_e32 v9, v14
	v_mov_b32_e32 v14, v11
	v_pk_mul_f32 v[6:7], v[6:7], v[44:45]
	v_pk_mul_f32 v[4:5], v[4:5], v[12:13]
	v_pk_mul_f32 v[0:1], v[0:1], v[8:9]
	v_pk_mul_f32 v[2:3], v[2:3], v[14:15]
	v_pk_mul_f32 v[8:9], v[6:7], v[40:41]
	v_pk_mul_f32 v[10:11], v[4:5], v[42:43]
	v_pk_mul_f32 v[12:13], v[0:1], v[48:49]
	v_pk_mul_f32 v[14:15], v[2:3], v[50:51]
	v_pk_mul_f32 v[4:5], v[4:5], v[42:43] op_sel:[1,0] op_sel_hi:[0,1]
	v_pk_mul_f32 v[0:1], v[0:1], v[48:49] op_sel:[1,0] op_sel_hi:[0,1]
	v_pk_mul_f32 v[6:7], v[6:7], v[40:41] op_sel:[1,0] op_sel_hi:[0,1]
	v_pk_mul_f32 v[2:3], v[2:3], v[50:51] op_sel:[1,0] op_sel_hi:[0,1]
	v_sub_f32_e32 v8, v8, v9
	v_sub_f32_e32 v9, v10, v11
	v_sub_f32_e32 v10, v12, v13
	v_sub_f32_e32 v11, v14, v15
	v_add_f32_e32 v4, v4, v5
	v_add_f32_e32 v5, v0, v1
	v_cvt_pk_bf16_f32 v0, v8, v9
	v_cvt_pk_bf16_f32 v1, v10, v11
	v_add_f32_e32 v6, v6, v7
	v_add_f32_e32 v2, v2, v3
	ds_write_b64 v21, v[0:1] offset:272
	v_cvt_pk_bf16_f32 v0, v6, v4
	v_cvt_pk_bf16_f32 v1, v5, v2
	ds_write_b64 v21, v[0:1] offset:336
	flat_load_dwordx4 v[12:15], v[36:37] offset:1856
	flat_load_dwordx4 v[8:11], v[36:37] offset:1984
	flat_load_dwordx4 v[0:3], v[28:29] offset:128
	flat_load_dwordx4 v[4:7], v[28:29] offset:144
	v_or_b32_e32 v44, 64, v33
	v_or_b32_e32 v45, 0x80, v33
	v_mul_lo_u16_e32 v42, 43, v44
	v_mul_lo_u16_e32 v43, 0xab, v45
	v_lshrrev_b16_e32 v66, 10, v42
	v_lshrrev_b16_e32 v67, 12, v43
	v_or_b32_e32 v48, 0x100, v33
	v_or_b32_e32 v49, 0x180, v33
	v_or_b32_e32 v50, 0x140, v33
	v_or_b32_e32 v51, 0x200, v33
	v_mul_u32_u24_e32 v57, 0xaab, v48
	v_mul_u32_u24_e32 v58, 0xaab, v50
	v_mul_u32_u24_e32 v59, 0xaab, v49
	v_mul_u32_u24_e32 v61, 0xaab, v51
	v_mad_i32_i24 v33, v35, s58, v33
	v_lshrrev_b32_e32 v57, 16, v57
	v_lshrrev_b32_e32 v68, 16, v58
	v_lshrrev_b32_e32 v69, 16, v59
	v_perm_b32 v58, v59, v58, s44
	v_lshrrev_b32_e32 v59, 16, v60
	v_lshrrev_b32_e32 v70, 16, v61
	v_perm_b32 v60, v61, v60, s44
	v_lshrrev_b32_e32 v61, 16, v62
	v_perm_b32 v62, v63, v62, s44
	v_lshrrev_b32_e32 v63, 16, v64
	v_lshlrev_b32_e32 v64, 4, v33
	v_mul_u32_u24_e32 v35, 0x300, v35
	v_lshlrev_b32_e32 v184, 1, v35
	v_mov_b32_e32 v35, v30
	v_mov_b64_e32 v[40:41], s[14:15]
	v_mad_i64_i32 v[40:41], s[2:3], v99, s39, v[40:41]
	v_lshl_add_u64 v[40:41], v[40:41], 0, s[22:23]
	v_mad_i32_i24 v55, v63, s58, v55
	v_lshlrev_b32_e32 v80, 4, v55
	s_waitcnt vmcnt(0) lgkmcnt(0)
; #define LDSP(T) __attribute__((address_space(3))) T*
; template <int NCH, int STRIDE> DEV void slab_flush(char* slab, u16* grow0, int gstride, int lane) {
;   asm volatile("s_waitcnt lgkmcnt(0)" ::: "memory");
; #pragma unroll
;   for (int i = 0; i < NCH / 2; ++i) {
;     const int q = i * 64 + lane, row = q / NCH, cc = q - row * NCH;
;     const u32x4 v = *(LDSP(const u32x4))(slab + row * STRIDE + cc * 16);
;     *reinterpret_cast<u32x4*>(grow0 + (long)row * gstride + cc * 8) = v;
;   }
; DEV void epi_uq(f32x16 (&acc)[1][6], const Params& P, int layer, int batch, int m0, int head, int wid, int r32, int hi, char* lds) {
;     ...
;   for (int r4 = 0; r4 < 4; ++r4) {
;     const int i = r4 * 8 + hi * 4;
;     const float4 g1 = *reinterpret_cast<const float4*>(g + 128 + i), g2 = *reinterpret_cast<const float4*>(g + 160 + i);
;     const float4 cs01 = *reinterpret_cast<const float4*>(rp + i), cs23 = *reinterpret_cast<const float4*>(rp + i + 2);
;     const float x1[4] = {acc[0][4][r4 * 4] * inv * g1.x, acc[0][4][r4 * 4 + 1] * inv * g1.y, acc[0][4][r4 * 4 + 2] * inv * g1.z, acc[0][4][r4 * 4 + 3] * inv * g1.w};
;     const float x2[4] = {acc[0][5][r4 * 4] * inv * g2.x, acc[0][5][r4 * 4 + 1] * inv * g2.y, acc[0][5][r4 * 4 + 2] * inv * g2.z, acc[0][5][r4 * 4 + 3] * inv * g2.w};
;     const float cc[4] = {cs01.x, cs01.z, cs23.x, cs23.z}, sn[4] = {cs01.y, cs01.w, cs23.y, cs23.w};
;     st4lds(dst, 128 + i, x1[0] * cc[0] - x2[0] * sn[0], x1[1] * cc[1] - x2[1] * sn[1], x1[2] * cc[2] - x2[2] * sn[2], x1[3] * cc[3] - x2[3] * sn[3]);
;     st4lds(dst, 160 + i, x1[0] * sn[0] + x2[0] * cc[0], x1[1] * sn[1] + x2[1] * cc[1], x1[2] * sn[2] + x2[2] * cc[2], x1[3] * sn[3] + x2[3] * cc[3]);
;   }
;   slab_flush<24, 400>(slab, WS{P.ws}.QB() + (long)(m0 + wid * 32) * 768 + head * 192, 768, hi * 32 + r32);
	v_mov_b32_e32 v42, v12
	v_mov_b32_e32 v43, v8
	v_mov_b32_e32 v8, v13
	v_mov_b32_e32 v12, v14
	v_mov_b32_e32 v13, v10
	v_mov_b32_e32 v10, v15
	v_pk_mul_f32 v[14:15], v[38:39], v[42:43]
	v_pk_mul_f32 v[8:9], v[24:25], v[8:9]
	v_pk_mul_f32 v[12:13], v[22:23], v[12:13]
	v_pk_mul_f32 v[10:11], v[26:27], v[10:11]
	v_pk_mul_f32 v[22:23], v[14:15], v[0:1]
	v_pk_mul_f32 v[24:25], v[8:9], v[2:3]
	v_pk_mul_f32 v[26:27], v[12:13], v[4:5]
	v_pk_mul_f32 v[38:39], v[10:11], v[6:7]
	v_pk_mul_f32 v[0:1], v[14:15], v[0:1] op_sel:[1,0] op_sel_hi:[0,1]
	v_pk_mul_f32 v[2:3], v[8:9], v[2:3] op_sel:[1,0] op_sel_hi:[0,1]
	v_pk_mul_f32 v[4:5], v[12:13], v[4:5] op_sel:[1,0] op_sel_hi:[0,1]
	v_pk_mul_f32 v[6:7], v[10:11], v[6:7] op_sel:[1,0] op_sel_hi:[0,1]
	v_sub_f32_e32 v8, v22, v23
	v_sub_f32_e32 v9, v24, v25
	v_sub_f32_e32 v10, v26, v27
	v_sub_f32_e32 v11, v38, v39
	v_add_f32_e32 v12, v0, v1
	v_cvt_pk_bf16_f32 v0, v8, v9
	v_cvt_pk_bf16_f32 v1, v10, v11
	v_add_f32_e32 v2, v2, v3
	v_add_f32_e32 v3, v4, v5
	v_add_f32_e32 v4, v6, v7
	ds_write_b64 v21, v[0:1] offset:288
	v_cvt_pk_bf16_f32 v0, v12, v2
	v_cvt_pk_bf16_f32 v1, v3, v4
	ds_write_b64 v21, v[0:1] offset:352
	flat_load_dwordx4 v[0:3], v[36:37] offset:1888
	flat_load_dwordx4 v[4:7], v[36:37] offset:2016
	flat_load_dwordx4 v[8:11], v[28:29] offset:192
	flat_load_dwordx4 v[12:15], v[28:29] offset:208
	v_lshlrev_b32_e32 v22, 3, v33
	v_mad_i32_i24 v24, v66, s58, v44
	v_mad_i32_i24 v33, v56, s58, v47
	v_mad_i32_i24 v29, v57, s58, v48
	v_mul_u32_u24_e32 v25, 0x190, v66
	v_mad_i32_i24 v26, v67, s58, v45
	v_mul_u32_u24_e32 v27, 0x190, v67
	v_mul_u32_u24_e32 v45, 0x300, v67
	v_mul_u32_u24_e32 v39, 0x190, v57
	v_pk_mul_lo_u16 v42, v58, s37 op_sel_hi:[1,0]
	v_mad_i32_i24 v43, v69, s58, v49
	v_mad_i32_i24 v44, v59, s58, v52
	v_mad_i32_i24 v52, v71, s58, v53
	v_add3_u32 v53, v46, v65, v64
	v_lshlrev_b32_e32 v64, 4, v24
	v_lshlrev_b32_e32 v67, 4, v33
	v_lshlrev_b32_e32 v28, 3, v33
	v_lshlrev_b32_e32 v33, 4, v29
	v_mul_u32_u24_e32 v37, 0x190, v56
	v_mul_u32_u24_e32 v47, 0x300, v56
	v_mul_u32_u24_e32 v56, 0x300, v57
	v_mad_i32_i24 v38, v68, s58, v50
	v_mul_u32_u24_e32 v57, 0x300, v68
	v_pk_mul_lo_u16 v48, v60, s37 op_sel_hi:[1,0]
	v_mad_i32_i24 v49, v70, s58, v51
	v_mul_u32_u24_e32 v60, 0x300, v70
	v_mad_i32_i24 v50, v61, s58, v54
	v_mul_u32_u24_e32 v54, 0x300, v61
	v_mul_u32_u24_e32 v61, 0x300, v71
	v_and_b32_e32 v68, 0xfff0, v42
	v_lshrrev_b32_e32 v70, 16, v42
	v_lshlrev_b32_e32 v71, 4, v43
	v_lshlrev_b32_e32 v42, 3, v43
	v_add3_u32 v43, v46, v25, v64
	v_add3_u32 v64, v46, v39, v33
	v_mov_b32_e32 v33, v31
	v_pk_mul_f32 v[30:31], v[34:35], v[20:21] op_sel_hi:[1,0]
	v_pk_mul_f32 v[32:33], v[32:33], v[20:21] op_sel_hi:[1,0]
	v_ashrrev_i32_e32 v23, 31, v22
	v_mul_u32_u24_e32 v66, 0x300, v66
	v_lshlrev_b32_e32 v24, 3, v24
	v_ashrrev_i32_e32 v25, 31, v24
	v_lshlrev_b32_e32 v65, 4, v26
	v_and_b32_e32 v72, 0xfff0, v48
	v_lshrrev_b32_e32 v74, 16, v48
	v_lshlrev_b32_e32 v75, 4, v49
	v_lshlrev_b32_e32 v48, 3, v49
	v_add3_u32 v49, v46, v27, v65
	v_lshlrev_b32_e32 v26, 3, v26
	v_ashrrev_i32_e32 v27, 31, v26
	v_pk_mul_lo_u16 v51, v62, s37 op_sel_hi:[1,0]
	v_lshlrev_b32_e32 v36, 3, v29
	v_and_b32_e32 v76, 0xfff0, v51
	v_lshrrev_b32_e32 v78, 16, v51
	v_add3_u32 v51, v46, v37, v67
	v_ashrrev_i32_e32 v29, 31, v28
	v_ashrrev_i32_e32 v37, 31, v36
	v_mul_u32_u24_e32 v58, 0x300, v69
	v_lshlrev_b32_e32 v69, 4, v38
	v_add3_u32 v65, v46, v68, v69
	v_lshlrev_b32_e32 v38, 3, v38
	v_ashrrev_i32_e32 v39, 31, v38
	v_lshlrev_b32_e32 v73, 4, v44
	v_mul_u32_u24_e32 v59, 0x300, v59
	v_lshlrev_b32_e32 v44, 3, v44
	v_lshlrev_b32_e32 v77, 4, v50
	v_lshlrev_b32_e32 v50, 3, v50
	v_lshlrev_b32_e32 v79, 4, v52
	v_lshlrev_b32_e32 v52, 3, v52
	v_mul_u32_u24_e32 v62, 0x190, v63
	v_mul_u32_u24_e32 v63, 0x300, v63
	s_waitcnt vmcnt(0) lgkmcnt(0)
	v_mov_b32_e32 v34, v0
	v_mov_b32_e32 v35, v4
	v_mov_b32_e32 v4, v1
	v_mov_b32_e32 v0, v2
	v_mov_b32_e32 v1, v6
	v_mov_b32_e32 v6, v3
	v_pk_mul_f32 v[2:3], v[16:17], v[34:35]
	v_pk_mul_f32 v[4:5], v[18:19], v[4:5]
	v_pk_mul_f32 v[0:1], v[30:31], v[0:1]
	v_pk_mul_f32 v[6:7], v[32:33], v[6:7]
	v_pk_mul_f32 v[16:17], v[2:3], v[8:9]
	v_pk_mul_f32 v[18:19], v[4:5], v[10:11]
	v_pk_mul_f32 v[30:31], v[0:1], v[12:13]
	v_pk_mul_f32 v[32:33], v[6:7], v[14:15]
	v_pk_mul_f32 v[2:3], v[2:3], v[8:9] op_sel:[1,0] op_sel_hi:[0,1]
	v_pk_mul_f32 v[4:5], v[4:5], v[10:11] op_sel:[1,0] op_sel_hi:[0,1]
	v_pk_mul_f32 v[0:1], v[0:1], v[12:13] op_sel:[1,0] op_sel_hi:[0,1]
	v_pk_mul_f32 v[6:7], v[6:7], v[14:15] op_sel:[1,0] op_sel_hi:[0,1]
	v_sub_f32_e32 v8, v16, v17
	v_sub_f32_e32 v9, v18, v19
	v_sub_f32_e32 v10, v30, v31
	v_sub_f32_e32 v11, v32, v33
	v_add_f32_e32 v2, v2, v3
	v_add_f32_e32 v3, v4, v5
	v_add_f32_e32 v4, v0, v1
	v_cvt_pk_bf16_f32 v0, v8, v9
	v_cvt_pk_bf16_f32 v1, v10, v11
	v_add_f32_e32 v5, v6, v7
	ds_write_b64 v21, v[0:1] offset:304
	v_cvt_pk_bf16_f32 v0, v2, v3
	v_cvt_pk_bf16_f32 v1, v4, v5
	ds_write_b64 v21, v[0:1] offset:368
	s_waitcnt lgkmcnt(0)
	ds_read_b128 v[0:3], v53
	v_lshl_add_u64 v[4:5], v[40:41], 0, v[184:185]
	v_lshl_add_u64 v[4:5], v[22:23], 1, v[4:5]
	v_lshlrev_b32_e32 v184, 1, v66
	v_add3_u32 v6, v46, v70, v71
	s_waitcnt lgkmcnt(0)
	flat_store_dwordx4 v[4:5], v[0:3]
	ds_read_b128 v[0:3], v43
	v_lshl_add_u64 v[4:5], v[40:41], 0, v[184:185]
	v_lshl_add_u64 v[4:5], v[24:25], 1, v[4:5]
	v_lshlrev_b32_e32 v184, 1, v45
	v_ashrrev_i32_e32 v43, 31, v42
	s_waitcnt lgkmcnt(0)
	flat_store_dwordx4 v[4:5], v[0:3]
	ds_read_b128 v[0:3], v49
	v_lshl_add_u64 v[4:5], v[40:41], 0, v[184:185]
	v_lshl_add_u64 v[4:5], v[26:27], 1, v[4:5]
	v_lshlrev_b32_e32 v184, 1, v47
	v_add3_u32 v7, v46, v72, v73
	s_waitcnt lgkmcnt(0)
; #define LDSP(T) __attribute__((address_space(3))) T*
; #define GLOAD(kt, buf) do { _Pragma("unroll") for (int i = 0; i < 4; ++i) glds16(Ap + (long)i * 64 * lda + (kt) * 64, As + (buf) * 32768 + soff + i * 8192); \
;     _Pragma("unroll") for (int i = 0; i < NB; ++i) glds16(Bp + (long)i * 64 * ldb + (kt) * 64, Bs + (buf) * 32768 + soff + i * 8192); } while (0)
; template <int NCH, int STRIDE> DEV void slab_flush(char* slab, u16* grow0, int gstride, int lane) {
;   asm volatile("s_waitcnt lgkmcnt(0)" ::: "memory");
; #pragma unroll
;   for (int i = 0; i < NCH / 2; ++i) {
;     const int q = i * 64 + lane, row = q / NCH, cc = q - row * NCH;
;     const u32x4 v = *(LDSP(const u32x4))(slab + row * STRIDE + cc * 16);
;     *reinterpret_cast<u32x4*>(grow0 + (long)row * gstride + cc * 8) = v;
;   }
;   asm volatile("s_waitcnt lgkmcnt(0)" ::: "memory");
; }
; template <int WM, int WN, int BN, int EPI>
; DEV void gemm_tile(const u16* __restrict__ A, int lda, const u16* __restrict__ Bt, int ldb, int K, int m0, char* lds,
;                    const Params& P, int layer, int batch, int nt) {
;     ...
;   const int srow = tid >> 3, sch = (tid & 7) ^ ((srow >> 1) & 7);
;   const u16* Ap = A + (long)(m0 + srow) * lda + sch * 8;
;   const u16* Bp = Bt + (long)srow * ldb + sch * 8;
;   const int soff = tid * 16;
;     ...
;   GLOAD(0, 0); asm volatile("s_waitcnt vmcnt(0)" ::: "memory"); __syncthreads();
	flat_store_dwordx4 v[4:5], v[0:3]
	ds_read_b128 v[0:3], v51
	v_lshl_add_u64 v[4:5], v[40:41], 0, v[184:185]
	v_lshl_add_u64 v[4:5], v[28:29], 1, v[4:5]
	v_lshlrev_b32_e32 v184, 1, v56
	v_ashrrev_i32_e32 v45, 31, v44
	s_waitcnt lgkmcnt(0)
	flat_store_dwordx4 v[4:5], v[0:3]
	ds_read_b128 v[0:3], v64
	v_lshl_add_u64 v[4:5], v[40:41], 0, v[184:185]
	v_lshl_add_u64 v[4:5], v[36:37], 1, v[4:5]
	v_lshlrev_b32_e32 v184, 1, v57
	v_add3_u32 v8, v46, v74, v75
	s_waitcnt lgkmcnt(0)
	flat_store_dwordx4 v[4:5], v[0:3]
	ds_read_b128 v[0:3], v65
	v_lshl_add_u64 v[4:5], v[40:41], 0, v[184:185]
	v_lshl_add_u64 v[4:5], v[38:39], 1, v[4:5]
	v_lshlrev_b32_e32 v184, 1, v58
	v_ashrrev_i32_e32 v49, 31, v48
	s_waitcnt lgkmcnt(0)
	flat_store_dwordx4 v[4:5], v[0:3]
	ds_read_b128 v[0:3], v6
	v_lshl_add_u64 v[4:5], v[40:41], 0, v[184:185]
	v_lshl_add_u64 v[4:5], v[42:43], 1, v[4:5]
	v_lshlrev_b32_e32 v184, 1, v59
	v_add3_u32 v6, v46, v76, v77
	s_waitcnt lgkmcnt(0)
	flat_store_dwordx4 v[4:5], v[0:3]
	ds_read_b128 v[0:3], v7
	v_lshl_add_u64 v[4:5], v[40:41], 0, v[184:185]
	v_lshl_add_u64 v[4:5], v[44:45], 1, v[4:5]
	v_lshlrev_b32_e32 v184, 1, v60
	v_ashrrev_i32_e32 v51, 31, v50
	s_waitcnt lgkmcnt(0)
	flat_store_dwordx4 v[4:5], v[0:3]
	ds_read_b128 v[0:3], v8
	v_lshl_add_u64 v[4:5], v[40:41], 0, v[184:185]
	v_lshl_add_u64 v[4:5], v[48:49], 1, v[4:5]
	v_lshlrev_b32_e32 v184, 1, v54
	v_add3_u32 v7, v46, v78, v79
	s_waitcnt lgkmcnt(0)
	flat_store_dwordx4 v[4:5], v[0:3]
	ds_read_b128 v[0:3], v6
	v_lshl_add_u64 v[4:5], v[40:41], 0, v[184:185]
	v_lshl_add_u64 v[4:5], v[50:51], 1, v[4:5]
	v_lshlrev_b32_e32 v184, 1, v61
	v_ashrrev_i32_e32 v53, 31, v52
	s_waitcnt lgkmcnt(0)
	flat_store_dwordx4 v[4:5], v[0:3]
	ds_read_b128 v[0:3], v7
	v_lshl_add_u64 v[4:5], v[40:41], 0, v[184:185]
	v_lshl_add_u64 v[4:5], v[52:53], 1, v[4:5]
	v_add3_u32 v6, v46, v62, v80
	v_lshlrev_b32_e32 v184, 1, v63
	s_waitcnt lgkmcnt(0)
	flat_store_dwordx4 v[4:5], v[0:3]
	ds_read_b128 v[0:3], v6
	v_lshlrev_b32_e32 v6, 3, v55
	v_lshl_add_u64 v[4:5], v[40:41], 0, v[184:185]
	v_ashrrev_i32_e32 v7, 31, v6
	v_lshl_add_u64 v[4:5], v[6:7], 1, v[4:5]
	s_waitcnt lgkmcnt(0)
	flat_store_dwordx4 v[4:5], v[0:3]
	s_waitcnt lgkmcnt(0)
	s_waitcnt lgkmcnt(0)
	s_barrier
	s_cbranch_execnz .LBB0_355
.LBB0_359:
	s_lshl_b32 s2, s54, 16
	s_or_b32 s2, s2, s53
	s_add_u32 s60, s48, s2
	v_mov_b32_e32 v152, v226
	s_addc_u32 s61, s52, 0
	s_lshl_b32 s2, s55, 8
	s_mov_b64 s[62:63], 0xc000
	v_ashrrev_i32_e32 v0, 3, v152
	v_lshrrev_b32_e32 v1, 4, v152
	v_xor_b32_e32 v1, v1, v152
	v_add_u32_e32 v2, s2, v0
	v_ashrrev_i32_e32 v3, 31, v2
	v_lshlrev_b32_e32 v1, 4, v1
	v_lshlrev_b32_e32 v156, 4, v152
	v_lshlrev_b64 v[2:3], 8, v[2:3]
	v_and_b32_e32 v184, 0x70, v1
	v_ashrrev_i32_e32 v1, 31, v0
	v_add_u32_e32 v148, 0, v156
	v_lshl_add_u64 v[2:3], s[16:17], 0, v[2:3]
	v_lshlrev_b64 v[0:1], 8, v[0:1]
	v_readfirstlane_b32 s3, v148
	v_add_u32_e32 v5, 0x2000, v148
	v_lshl_add_u64 v[128:129], v[2:3], 0, v[184:185]
	v_lshl_add_u64 v[0:1], s[60:61], 0, v[0:1]
	s_mov_b32 m0, s3
	s_mov_b64 s[60:61], 0x4000
	v_readfirstlane_b32 s3, v5
	v_add_u32_e32 v5, 0x4000, v148
	global_load_lds_dwordx4 v[128:129], off
	v_lshl_add_u64 v[2:3], v[128:129], 0, s[60:61]
	s_mov_b32 m0, s3
	v_readfirstlane_b32 s3, v5
	v_add_u32_e32 v5, 0x6000, v148
	global_load_lds_dwordx4 v[2:3], off
	v_lshl_add_u64 v[2:3], v[128:129], 0, s[40:41]
	s_mov_b32 m0, s3
	v_readfirstlane_b32 s3, v5
	global_load_lds_dwordx4 v[2:3], off
	v_lshl_add_u64 v[2:3], v[128:129], 0, s[62:63]
	s_mov_b32 m0, s3
	s_add_i32 s3, 0, 0x10000
	global_load_lds_dwordx4 v[2:3], off
	v_add_u32_e32 v2, s3, v156
	v_add_u32_e32 v3, 0x2000, v2
	v_readfirstlane_b32 s22, v2
	v_lshl_add_u64 v[130:131], v[0:1], 0, v[184:185]
	s_mov_b32 m0, s22
	v_readfirstlane_b32 s22, v3
	v_add_u32_e32 v3, 0x4000, v2
	global_load_lds_dwordx4 v[130:131], off
	v_lshl_add_u64 v[0:1], v[130:131], 0, s[60:61]
	s_mov_b32 m0, s22
	v_readfirstlane_b32 s22, v3
	v_add_u32_e32 v2, 0x6000, v2
	global_load_lds_dwordx4 v[0:1], off
	v_lshl_add_u64 v[0:1], v[130:131], 0, s[40:41]
	s_mov_b32 m0, s22
	v_readfirstlane_b32 s22, v2
	v_and_b32_e32 v154, 31, v152
	global_load_lds_dwordx4 v[0:1], off
	v_lshl_add_u64 v[0:1], v[130:131], 0, s[62:63]
	s_mov_b32 m0, s22
	v_add_u32_e32 v5, 0x8000, v148
	global_load_lds_dwordx4 v[0:1], off
	v_lshlrev_b32_e32 v1, 7, v154
	v_add_u32_e32 v153, s3, v1
	s_add_i32 s3, 0, 0x18000
	v_ashrrev_i32_e32 v149, 6, v152
	v_add_u32_e32 v157, s3, v156
	v_readfirstlane_b32 s3, v5
	v_lshlrev_b32_e32 v0, 12, v149
	v_lshl_add_u64 v[2:3], v[128:129], 0, s[30:31]
	s_mov_b32 m0, s3
	v_readfirstlane_b32 s3, v157
	s_waitcnt vmcnt(0)
	s_waitcnt vmcnt(0) lgkmcnt(0)
	s_barrier
; #define SBAR() __builtin_amdgcn_sched_barrier(0)
; DEV void glds16(const u16* g, char* l) { __builtin_amdgcn_global_load_lds((const unsigned*)g, (unsigned*)l, 16, 0, 0); }
; template <int WM, int WN, int BN, int EPI>
; DEV void gemm_tile(const u16* __restrict__ A, int lda, const u16* __restrict__ Bt, int ldb, int K, int m0, char* lds,
;                    const Params& P, int layer, int batch, int nt) {
;     ...
;   for (int kt = 0; kt < nk; ++kt) {
;     const bool more = kt + 1 < nk;
;     const int nb = (kt + 1) & 1;
;     const char* as = As + (kt & 1) * 32768; const char* bs = Bs + (kt & 1) * 32768;
; #pragma unroll
;     for (int ks = 0; ks < 4; ++ks) {
;       if (more) { glds16(Ap + (long)ks * 64 * lda + (kt + 1) * 64, As + nb * 32768 + soff + ks * 8192);
;                   if (ks < NB) glds16(Bp + (long)ks * 64 * ldb + (kt + 1) * 64, Bs + nb * 32768 + soff + ks * 8192); }
;       SBAR();
;       bf16x8 xf[MI], wf[NI];
; #pragma unroll
;       for (int mi = 0; mi < MI; ++mi) xf[mi] = *reinterpret_cast<const bf16x8*>(as + swz128(wm * (MI * 32) + mi * 32 + r32, ks * 2 + hi));
; #pragma unroll
;       for (int ni = 0; ni < NI; ++ni) wf[ni] = *reinterpret_cast<const bf16x8*>(bs + swz128(wn * (NI * 32) + ni * 32 + r32, ks * 2 + hi));
; #pragma unroll
;       for (int mi = 0; mi < MI; ++mi)
; #pragma unroll
;         for (int ni = 0; ni < NI; ++ni) acc[mi][ni] = __builtin_amdgcn_mfma_f32_32x32x16_bf16(wf[ni], xf[mi], acc[mi][ni], 0, 0, 0);
;     }
	v_add3_u32 v151, 0, v0, v1
	v_lshl_add_u64 v[0:1], v[130:131], 0, s[30:31]
	global_load_lds_dwordx4 v[2:3], off
	s_mov_b32 m0, s3
	v_lshrrev_b32_e32 v4, 5, v152
	global_load_lds_dwordx4 v[0:1], off
	v_bfe_u32 v155, v152, 5, 1
	v_bfe_u32 v150, v152, 1, 3
	v_bitop3_b32 v0, v4, v150, 1 bitop3:0x6c
	v_lshlrev_b32_e32 v4, 4, v0
	v_add_u32_e32 v158, v153, v4
	ds_read_b128 v[194:197], v158
	v_add_u32_e32 v159, v151, v4
	ds_read_b128 v[198:201], v159
	ds_read_b128 v[202:205], v158 offset:4096
	ds_read_b128 v[206:209], v158 offset:8192
	ds_read_b128 v[210:213], v158 offset:12288
	ds_read_b128 v[214:217], v158 offset:16384
	ds_read_b128 v[218:221], v158 offset:20480
	ds_read_b128 v[222:225], v158 offset:24576
	ds_read_b128 v[232:235], v158 offset:28672
	v_add_u32_e32 v133, 0xa000, v148
	s_mov_b64 s[60:61], 0x4080
	v_add_u32_e32 v132, 0x2000, v157
	v_readfirstlane_b32 s3, v133
	v_lshl_add_u64 v[78:79], v[128:129], 0, s[60:61]
	s_mov_b32 m0, s3
	s_waitcnt lgkmcnt(7)
	v_mfma_f32_32x32x16_bf16 v[48:63], v[194:197], v[198:201], 0
	v_readfirstlane_b32 s3, v132
	v_lshl_add_u64 v[76:77], v[130:131], 0, s[60:61]
	s_waitcnt lgkmcnt(5)
	v_mfma_f32_32x32x16_bf16 v[32:47], v[202:205], v[198:201], 0
	s_waitcnt lgkmcnt(3)
	v_mfma_f32_32x32x16_bf16 v[112:127], v[214:217], v[198:201], 0
	s_waitcnt lgkmcnt(1)
	v_mfma_f32_32x32x16_bf16 v[96:111], v[218:221], v[198:201], 0
	global_load_lds_dwordx4 v[78:79], off
	s_mov_b32 m0, s3
	s_nop 0
	global_load_lds_dwordx4 v[76:77], off
	v_mfma_f32_32x32x16_bf16 v[16:31], v[206:209], v[198:201], 0
	v_mfma_f32_32x32x16_bf16 v[0:15], v[210:213], v[198:201], 0
	v_mfma_f32_32x32x16_bf16 v[80:95], v[222:225], v[198:201], 0
	s_waitcnt lgkmcnt(0)
	v_mfma_f32_32x32x16_bf16 v[64:79], v[232:235], v[198:201], 0
	v_bitop3_b32 v132, v155, v150, 2 bitop3:0x36
	v_lshlrev_b32_e32 v136, 4, v132
	v_add_u32_e32 v160, v153, v136
	ds_read_b128 v[236:239], v160
	v_add_u32_e32 v161, v151, v136
	ds_read_b128 v[240:243], v161
	ds_read_b128 v[244:247], v160 offset:4096
	ds_read_b128 v[248:251], v160 offset:8192
	ds_read_b128 v[170:173], v160 offset:12288
	ds_read_b128 v[174:177], v160 offset:16384
	ds_read_b128 v[178:181], v160 offset:20480
	ds_read_b128 v[194:197], v160 offset:24576
	ds_read_b128 v[198:201], v160 offset:28672
	v_add_u32_e32 v163, 0xc000, v148
	v_add_u32_e32 v162, 0x4000, v157
	v_readfirstlane_b32 s3, v163
	v_lshl_add_u64 v[146:147], v[128:129], 0, s[42:43]
	s_mov_b32 m0, s3
	v_readfirstlane_b32 s3, v162
	s_waitcnt lgkmcnt(7)
	v_mfma_f32_32x32x16_bf16 v[48:63], v[236:239], v[240:243], v[48:63]
	v_lshl_add_u64 v[144:145], v[130:131], 0, s[42:43]
	s_waitcnt lgkmcnt(5)
	v_mfma_f32_32x32x16_bf16 v[32:47], v[244:247], v[240:243], v[32:47]
	v_mfma_f32_32x32x16_bf16 v[16:31], v[248:251], v[240:243], v[16:31]
	s_waitcnt lgkmcnt(3)
	v_mfma_f32_32x32x16_bf16 v[0:15], v[170:173], v[240:243], v[0:15]
	v_mfma_f32_32x32x16_bf16 v[112:127], v[174:177], v[240:243], v[112:127]
	s_waitcnt lgkmcnt(1)
	v_mfma_f32_32x32x16_bf16 v[96:111], v[178:181], v[240:243], v[96:111]
	global_load_lds_dwordx4 v[146:147], off
	s_mov_b32 m0, s3
	s_nop 0
	global_load_lds_dwordx4 v[144:145], off
	v_mfma_f32_32x32x16_bf16 v[80:95], v[194:197], v[240:243], v[80:95]
	s_waitcnt lgkmcnt(0)
	v_mfma_f32_32x32x16_bf16 v[64:79], v[198:201], v[240:243], v[64:79]
	v_bitop3_b32 v132, v155, v150, 4 bitop3:0x36
	v_lshlrev_b32_e32 v136, 4, v132
	v_add_u32_e32 v144, v153, v136
	ds_read_b128 v[202:205], v144
	v_add_u32_e32 v145, v151, v136
	ds_read_b128 v[206:209], v145
	ds_read_b128 v[210:213], v144 offset:4096
	ds_read_b128 v[214:217], v144 offset:8192
	ds_read_b128 v[218:221], v144 offset:12288
	ds_read_b128 v[222:225], v144 offset:16384
	ds_read_b128 v[232:235], v144 offset:20480
	ds_read_b128 v[236:239], v144 offset:24576
	ds_read_b128 v[240:243], v144 offset:28672
	v_add_u32_e32 v147, 0xe000, v148
	s_mov_b64 s[60:61], 0xc080
	v_add_u32_e32 v146, 0x6000, v157
	v_readfirstlane_b32 s3, v147
	v_lshl_add_u64 v[128:129], v[128:129], 0, s[60:61]
	s_mov_b32 m0, s3
	s_waitcnt lgkmcnt(7)
	v_mfma_f32_32x32x16_bf16 v[48:63], v[202:205], v[206:209], v[48:63]
	v_readfirstlane_b32 s3, v146
	v_lshl_add_u64 v[130:131], v[130:131], 0, s[60:61]
	s_waitcnt lgkmcnt(5)
	v_mfma_f32_32x32x16_bf16 v[32:47], v[210:213], v[206:209], v[32:47]
	v_mfma_f32_32x32x16_bf16 v[16:31], v[214:217], v[206:209], v[16:31]
	s_waitcnt lgkmcnt(3)
	v_mfma_f32_32x32x16_bf16 v[0:15], v[218:221], v[206:209], v[0:15]
	v_mfma_f32_32x32x16_bf16 v[112:127], v[222:225], v[206:209], v[112:127]
	s_waitcnt lgkmcnt(1)
	v_mfma_f32_32x32x16_bf16 v[96:111], v[232:235], v[206:209], v[96:111]
	global_load_lds_dwordx4 v[128:129], off
	s_mov_b32 m0, s3
	s_nop 0
	global_load_lds_dwordx4 v[130:131], off
	v_mfma_f32_32x32x16_bf16 v[80:95], v[236:239], v[206:209], v[80:95]
	s_waitcnt lgkmcnt(0)
	v_mfma_f32_32x32x16_bf16 v[64:79], v[240:243], v[206:209], v[64:79]
	v_bitop3_b32 v128, v155, v150, 6 bitop3:0x36
	v_lshlrev_b32_e32 v132, 4, v128
	v_add_u32_e32 v148, v153, v132
	ds_read_b128 v[244:247], v148
	v_add_u32_e32 v140, v151, v132
	ds_read_b128 v[248:251], v140
	ds_read_b128 v[170:173], v148 offset:4096
	ds_read_b128 v[174:177], v148 offset:8192
	ds_read_b128 v[178:181], v148 offset:12288
	ds_read_b128 v[194:197], v148 offset:16384
	ds_read_b128 v[198:201], v148 offset:20480
	ds_read_b128 v[202:205], v148 offset:24576
	ds_read_b128 v[206:209], v148 offset:28672
	s_waitcnt lgkmcnt(7)
	v_mfma_f32_32x32x16_bf16 v[48:63], v[244:247], v[248:251], v[48:63]
	s_waitcnt lgkmcnt(6)
	v_mfma_f32_32x32x16_bf16 v[32:47], v[170:173], v[248:251], v[32:47]
	s_waitcnt lgkmcnt(5)
	v_mfma_f32_32x32x16_bf16 v[16:31], v[174:177], v[248:251], v[16:31]
	s_waitcnt lgkmcnt(4)
	v_mfma_f32_32x32x16_bf16 v[0:15], v[178:181], v[248:251], v[0:15]
	s_waitcnt lgkmcnt(3)
	v_mfma_f32_32x32x16_bf16 v[112:127], v[194:197], v[248:251], v[112:127]
	s_waitcnt lgkmcnt(2)
	v_mfma_f32_32x32x16_bf16 v[96:111], v[198:201], v[248:251], v[96:111]
	s_waitcnt lgkmcnt(1)
	v_mfma_f32_32x32x16_bf16 v[80:95], v[202:205], v[248:251], v[80:95]
	s_waitcnt vmcnt(0)
	s_waitcnt vmcnt(0) lgkmcnt(0)
	s_barrier
; #define SBAR() __builtin_amdgcn_sched_barrier(0)
;   DEV float* ssq_ckv() const { return (float*)(b + O_SSQCKV); }
; DEV void glds16(const u16* g, char* l) { __builtin_amdgcn_global_load_lds((const unsigned*)g, (unsigned*)l, 16, 0, 0); }
; DEV void epi_ukv(f32x16 (&acc)[1][8], const Params& P, int layer, int batch, int m0, int head, int wid, int r32, int hi, char* lds) {
;   const int t = m0 + wid * 32 + r32;
;   const float rc = __builtin_amdgcn_rsqf((WS{P.ws}.ssq_ckv()[t] + WS{P.ws}.ssq_ckv()[TB + t]) * (1.f / 128.f) + EPS);
;   char* slab = lds + wid * 12800; char* vdst = slab + r32 * 272;
; template <int WM, int WN, int BN, int EPI>
; DEV void gemm_tile(const u16* __restrict__ A, int lda, const u16* __restrict__ Bt, int ldb, int K, int m0, char* lds,
;                    const Params& P, int layer, int batch, int nt) {
;     ...
;   for (int kt = 0; kt < nk; ++kt) {
;     const bool more = kt + 1 < nk;
;     const int nb = (kt + 1) & 1;
;     const char* as = As + (kt & 1) * 32768; const char* bs = Bs + (kt & 1) * 32768;
; #pragma unroll
;     for (int ks = 0; ks < 4; ++ks) {
;       if (more) { glds16(Ap + (long)ks * 64 * lda + (kt + 1) * 64, As + nb * 32768 + soff + ks * 8192);
;                   if (ks < NB) glds16(Bp + (long)ks * 64 * ldb + (kt + 1) * 64, Bs + nb * 32768 + soff + ks * 8192); }
;       SBAR();
;       bf16x8 xf[MI], wf[NI];
; #pragma unroll
;       for (int mi = 0; mi < MI; ++mi) xf[mi] = *reinterpret_cast<const bf16x8*>(as + swz128(wm * (MI * 32) + mi * 32 + r32, ks * 2 + hi));
; #pragma unroll
;       for (int ni = 0; ni < NI; ++ni) wf[ni] = *reinterpret_cast<const bf16x8*>(bs + swz128(wn * (NI * 32) + ni * 32 + r32, ks * 2 + hi));
; #pragma unroll
;       for (int mi = 0; mi < MI; ++mi)
; #pragma unroll
;         for (int ni = 0; ni < NI; ++ni) acc[mi][ni] = __builtin_amdgcn_mfma_f32_32x32x16_bf16(wf[ni], xf[mi], acc[mi][ni], 0, 0, 0);
;     }
;     asm volatile("s_waitcnt vmcnt(0)" ::: "memory");
;     __syncthreads();
	v_mfma_f32_32x32x16_bf16 v[64:79], v[206:209], v[248:251], v[64:79]
	ds_read_b128 v[210:213], v158 offset:32768
	ds_read_b128 v[214:217], v159 offset:32768
	ds_read_b128 v[218:221], v158 offset:36864
	ds_read_b128 v[222:225], v158 offset:40960
	ds_read_b128 v[232:235], v158 offset:45056
	ds_read_b128 v[236:239], v158 offset:49152
	ds_read_b128 v[240:243], v158 offset:53248
	ds_read_b128 v[244:247], v158 offset:57344
	ds_read_b128 v[248:251], v158 offset:61440
	ds_read_b128 v[170:173], v160 offset:32768
	s_waitcnt lgkmcnt(8)
	v_mfma_f32_32x32x16_bf16 v[48:63], v[210:213], v[214:217], v[48:63]
	ds_read_b128 v[174:177], v161 offset:32768
	s_waitcnt lgkmcnt(8)
	v_mfma_f32_32x32x16_bf16 v[32:47], v[218:221], v[214:217], v[32:47]
	ds_read_b128 v[178:181], v160 offset:36864
	s_waitcnt lgkmcnt(8)
	v_mfma_f32_32x32x16_bf16 v[16:31], v[222:225], v[214:217], v[16:31]
	ds_read_b128 v[194:197], v160 offset:40960
	s_waitcnt lgkmcnt(8)
	v_mfma_f32_32x32x16_bf16 v[0:15], v[232:235], v[214:217], v[0:15]
	ds_read_b128 v[198:201], v160 offset:45056
	s_waitcnt lgkmcnt(8)
	v_mfma_f32_32x32x16_bf16 v[112:127], v[236:239], v[214:217], v[112:127]
	ds_read_b128 v[202:205], v160 offset:49152
	s_waitcnt lgkmcnt(8)
	v_mfma_f32_32x32x16_bf16 v[96:111], v[240:243], v[214:217], v[96:111]
	ds_read_b128 v[206:209], v160 offset:53248
	s_waitcnt lgkmcnt(8)
	v_mfma_f32_32x32x16_bf16 v[80:95], v[244:247], v[214:217], v[80:95]
	ds_read_b128 v[210:213], v160 offset:57344
	s_waitcnt lgkmcnt(8)
	v_mfma_f32_32x32x16_bf16 v[64:79], v[248:251], v[214:217], v[64:79]
	ds_read_b128 v[214:217], v160 offset:61440
	ds_read_b128 v[218:221], v144 offset:32768
	s_waitcnt lgkmcnt(8)
	v_mfma_f32_32x32x16_bf16 v[48:63], v[170:173], v[174:177], v[48:63]
	ds_read_b128 v[222:225], v145 offset:32768
	s_waitcnt lgkmcnt(8)
	v_mfma_f32_32x32x16_bf16 v[32:47], v[178:181], v[174:177], v[32:47]
	ds_read_b128 v[232:235], v144 offset:36864
	s_waitcnt lgkmcnt(8)
	v_mfma_f32_32x32x16_bf16 v[16:31], v[194:197], v[174:177], v[16:31]
	ds_read_b128 v[236:239], v144 offset:40960
	s_waitcnt lgkmcnt(8)
	v_mfma_f32_32x32x16_bf16 v[0:15], v[198:201], v[174:177], v[0:15]
	ds_read_b128 v[240:243], v144 offset:45056
	s_waitcnt lgkmcnt(8)
	v_mfma_f32_32x32x16_bf16 v[112:127], v[202:205], v[174:177], v[112:127]
	ds_read_b128 v[244:247], v144 offset:49152
	s_waitcnt lgkmcnt(8)
	v_mfma_f32_32x32x16_bf16 v[96:111], v[206:209], v[174:177], v[96:111]
	ds_read_b128 v[248:251], v144 offset:53248
	s_waitcnt lgkmcnt(8)
	v_mfma_f32_32x32x16_bf16 v[80:95], v[210:213], v[174:177], v[80:95]
	ds_read_b128 v[170:173], v144 offset:57344
	s_waitcnt lgkmcnt(8)
	v_mfma_f32_32x32x16_bf16 v[64:79], v[214:217], v[174:177], v[64:79]
	ds_read_b128 v[174:177], v144 offset:61440
	ds_read_b128 v[178:181], v148 offset:49152
	s_waitcnt lgkmcnt(8)
	v_mfma_f32_32x32x16_bf16 v[48:63], v[218:221], v[222:225], v[48:63]
	ds_read_b128 v[194:197], v140 offset:32768
	s_waitcnt lgkmcnt(8)
	v_mfma_f32_32x32x16_bf16 v[32:47], v[232:235], v[222:225], v[32:47]
	ds_read_b128 v[198:201], v148 offset:45056
	s_waitcnt lgkmcnt(8)
	v_mfma_f32_32x32x16_bf16 v[16:31], v[236:239], v[222:225], v[16:31]
	ds_read_b128 v[202:205], v148 offset:32768
	s_waitcnt lgkmcnt(8)
	v_mfma_f32_32x32x16_bf16 v[0:15], v[240:243], v[222:225], v[0:15]
	ds_read_b128 v[206:209], v148 offset:53248
	s_waitcnt lgkmcnt(8)
	v_mfma_f32_32x32x16_bf16 v[112:127], v[244:247], v[222:225], v[112:127]
	s_waitcnt lgkmcnt(7)
	v_mfma_f32_32x32x16_bf16 v[96:111], v[248:251], v[222:225], v[96:111]
	s_waitcnt lgkmcnt(6)
	v_mfma_f32_32x32x16_bf16 v[80:95], v[170:173], v[222:225], v[80:95]
	s_waitcnt lgkmcnt(5)
	v_mfma_f32_32x32x16_bf16 v[64:79], v[174:177], v[222:225], v[64:79]
	v_lshlrev_b32_e32 v157, 3, v155
	s_waitcnt lgkmcnt(3)
	v_mfma_f32_32x32x16_bf16 v[112:127], v[178:181], v[194:197], v[112:127]
	ds_read_b128 v[144:147], v148 offset:36864
	ds_read_b128 v[136:139], v148 offset:40960
	ds_read_b128 v[162:165], v148 offset:57344
	ds_read_b128 v[166:169], v148 offset:61440
	v_lshl_add_u32 v148, v149, 5, s2
	v_or_b32_e32 v150, v148, v154
	v_ashrrev_i32_e32 v151, 31, v150
	s_waitcnt vmcnt(0)
	s_waitcnt lgkmcnt(0)
	s_barrier
	v_mfma_f32_32x32x16_bf16 v[96:111], v[206:209], v[194:197], v[96:111]
	v_lshl_add_u64 v[158:159], v[150:151], 2, s[18:19]
	v_add_co_u32_e32 v160, vcc, s93, v158
	s_nop 1
	v_addc_co_u32_e32 v161, vcc, 0, v159, vcc
	flat_load_dword v153, v[158:159]
	s_nop 0
	flat_load_dword v158, v[160:161]
	v_mfma_f32_32x32x16_bf16 v[80:95], v[162:165], v[194:197], v[80:95]
	v_mul_lo_u32 v149, v149, s99
	v_mul_u32_u24_e32 v159, 0x110, v154
	v_and_b32_e32 v184, 0xf0, v156
	s_lshl_b32 s22, s54, 8
	s_movk_i32 s2, 0xfff
	s_waitcnt vmcnt(0) lgkmcnt(0)
;   DEV u16* VB() const { return (u16*)(b + O_VB); }
;   DEV float* ssq_ckv() const { return (float*)(b + O_SSQCKV); }
; #define LDSP(T) __attribute__((address_space(3))) T*
; template <int NCH, int STRIDE> DEV void slab_flush(char* slab, u16* grow0, int gstride, int lane) {
;   asm volatile("s_waitcnt lgkmcnt(0)" ::: "memory");
; #pragma unroll
;   for (int i = 0; i < NCH / 2; ++i) {
;     const int q = i * 64 + lane, row = q / NCH, cc = q - row * NCH;
;     const u32x4 v = *(LDSP(const u32x4))(slab + row * STRIDE + cc * 16);
;     *reinterpret_cast<u32x4*>(grow0 + (long)row * gstride + cc * 8) = v;
;   }
;   asm volatile("s_waitcnt lgkmcnt(0)" ::: "memory");
; }
; DEV void epi_ukv(f32x16 (&acc)[1][8], const Params& P, int layer, int batch, int m0, int head, int wid, int r32, int hi, char* lds) {
;   const int t = m0 + wid * 32 + r32;
;   const float rc = __builtin_amdgcn_rsqf((WS{P.ws}.ssq_ckv()[t] + WS{P.ws}.ssq_ckv()[TB + t]) * (1.f / 128.f) + EPS);
;   char* slab = lds + wid * 12800; char* vdst = slab + r32 * 272;
; #pragma unroll
;   for (int ni = 4; ni < 8; ++ni)
; #pragma unroll
;     for (int r4 = 0; r4 < 4; ++r4) {
;       const f32x16& a = acc[0][ni];
;       st4lds(vdst, (ni - 4) * 32 + r4 * 8 + hi * 4, a[r4 * 4] * rc, a[r4 * 4 + 1] * rc, a[r4 * 4 + 2] * rc, a[r4 * 4 + 3] * rc);
;     }
;   slab_flush<16, 272>(slab, WS{P.ws}.VB() + (long)(m0 + wid * 32) * 512 + head * 128, 512, hi * 32 + r32);
	v_add_f32_e32 v153, v153, v158
	v_fmamk_f32 v153, v153, 0x3c000000, v227
	v_rsq_f32_e32 v158, v153
	v_add_u32_e32 v153, 0, v149
	v_add3_u32 v149, v153, v159, v157
	v_mfma_f32_32x32x16_bf16 v[64:79], v[166:169], v[194:197], v[64:79]
	v_mul_f32_e32 v112, v112, v158
	v_mul_f32_e32 v113, v113, v158
	v_mul_f32_e32 v114, v114, v158
	v_mul_f32_e32 v115, v115, v158
	v_mul_f32_e32 v159, v80, v158
	v_mul_f32_e32 v160, v81, v158
	v_cvt_pk_bf16_f32 v80, v112, v113
	v_cvt_pk_bf16_f32 v81, v114, v115
	v_mul_f32_e32 v116, v116, v158
	v_mul_f32_e32 v117, v117, v158
	v_mul_f32_e32 v118, v118, v158
	v_mul_f32_e32 v119, v119, v158
	ds_write_b64 v149, v[80:81]
	v_cvt_pk_bf16_f32 v80, v116, v117
	v_cvt_pk_bf16_f32 v81, v118, v119
	v_mul_f32_e32 v120, v120, v158
	v_mul_f32_e32 v121, v121, v158
	v_mul_f32_e32 v122, v122, v158
	v_mul_f32_e32 v123, v123, v158
	ds_write_b64 v149, v[80:81] offset:16
	v_cvt_pk_bf16_f32 v80, v120, v121
	v_cvt_pk_bf16_f32 v81, v122, v123
	v_mul_f32_e32 v124, v124, v158
	v_mul_f32_e32 v125, v125, v158
	v_mul_f32_e32 v126, v126, v158
	v_mul_f32_e32 v127, v127, v158
	ds_write_b64 v149, v[80:81] offset:32
	v_cvt_pk_bf16_f32 v80, v124, v125
	v_cvt_pk_bf16_f32 v81, v126, v127
	v_mul_f32_e32 v96, v96, v158
	v_mul_f32_e32 v97, v97, v158
	v_mul_f32_e32 v98, v98, v158
	v_mul_f32_e32 v99, v99, v158
	ds_write_b64 v149, v[80:81] offset:48
	v_cvt_pk_bf16_f32 v80, v96, v97
	v_cvt_pk_bf16_f32 v81, v98, v99
	v_mul_f32_e32 v100, v100, v158
	v_mul_f32_e32 v101, v101, v158
	v_mul_f32_e32 v102, v102, v158
	v_mul_f32_e32 v103, v103, v158
	ds_write_b64 v149, v[80:81] offset:64
	v_cvt_pk_bf16_f32 v80, v100, v101
	v_cvt_pk_bf16_f32 v81, v102, v103
	v_mul_f32_e32 v104, v104, v158
	v_mul_f32_e32 v105, v105, v158
	v_mul_f32_e32 v106, v106, v158
	v_mul_f32_e32 v107, v107, v158
	ds_write_b64 v149, v[80:81] offset:80
	v_cvt_pk_bf16_f32 v80, v104, v105
	v_cvt_pk_bf16_f32 v81, v106, v107
	v_mul_f32_e32 v108, v108, v158
	v_mul_f32_e32 v109, v109, v158
	v_mul_f32_e32 v110, v110, v158
	v_mul_f32_e32 v111, v111, v158
	ds_write_b64 v149, v[80:81] offset:96
	v_cvt_pk_bf16_f32 v80, v108, v109
	v_cvt_pk_bf16_f32 v81, v110, v111
	v_mul_f32_e32 v82, v82, v158
	v_mul_f32_e32 v83, v83, v158
	ds_write_b64 v149, v[80:81] offset:112
	v_cvt_pk_bf16_f32 v80, v159, v160
	v_cvt_pk_bf16_f32 v81, v82, v83
	v_mul_f32_e32 v84, v84, v158
	v_mul_f32_e32 v85, v85, v158
	v_mul_f32_e32 v86, v86, v158
	v_mul_f32_e32 v87, v87, v158
	ds_write_b64 v149, v[80:81] offset:128
	v_cvt_pk_bf16_f32 v80, v84, v85
	v_cvt_pk_bf16_f32 v81, v86, v87
	ds_write_b64 v149, v[80:81] offset:144
	v_mul_f32_e32 v80, v88, v158
	v_mul_f32_e32 v81, v89, v158
	v_mul_f32_e32 v82, v90, v158
	v_mul_f32_e32 v83, v91, v158
	v_cvt_pk_bf16_f32 v80, v80, v81
	v_cvt_pk_bf16_f32 v81, v82, v83
	ds_write_b64 v149, v[80:81] offset:160
	v_mul_f32_e32 v80, v92, v158
	v_mul_f32_e32 v81, v93, v158
	v_mul_f32_e32 v64, v64, v158
	v_mul_f32_e32 v65, v65, v158
	v_mul_f32_e32 v82, v94, v158
	v_mul_f32_e32 v83, v95, v158
	v_cvt_pk_bf16_f32 v80, v80, v81
	v_cvt_pk_bf16_f32 v81, v82, v83
	ds_write_b64 v149, v[80:81] offset:176
	v_mul_f32_e32 v66, v66, v158
	v_mul_f32_e32 v67, v67, v158
	v_cvt_pk_bf16_f32 v64, v64, v65
	v_cvt_pk_bf16_f32 v65, v66, v67
	ds_write_b64 v149, v[64:65] offset:192
	v_mul_f32_e32 v64, v68, v158
	v_mul_f32_e32 v65, v69, v158
	v_mul_f32_e32 v66, v70, v158
	v_mul_f32_e32 v67, v71, v158
	v_cvt_pk_bf16_f32 v64, v64, v65
	v_cvt_pk_bf16_f32 v65, v66, v67
	ds_write_b64 v149, v[64:65] offset:208
	v_mul_f32_e32 v64, v72, v158
	v_mul_f32_e32 v65, v73, v158
	v_mul_f32_e32 v66, v74, v158
	v_mul_f32_e32 v67, v75, v158
	v_cvt_pk_bf16_f32 v64, v64, v65
	v_cvt_pk_bf16_f32 v65, v66, v67
	ds_write_b64 v149, v[64:65] offset:224
	v_mul_f32_e32 v64, v76, v158
	v_mul_f32_e32 v65, v77, v158
	v_mul_f32_e32 v66, v78, v158
	v_mul_f32_e32 v67, v79, v158
	v_cvt_pk_bf16_f32 v64, v64, v65
	v_cvt_pk_bf16_f32 v65, v66, v67
	ds_write_b64 v149, v[64:65] offset:240
	v_ashrrev_i32_e32 v149, 31, v148
	v_lshlrev_b64 v[64:65], 10, v[148:149]
	v_bfe_u32 v70, v152, 4, 2
	v_lshl_add_u64 v[68:69], s[24:25], 0, v[64:65]
	v_mul_u32_u24_e32 v64, 0x110, v70
	s_waitcnt lgkmcnt(0)
	v_add3_u32 v72, v153, v184, v64
	ds_read_b128 v[64:67], v72
	v_lshl_add_u64 v[68:69], v[68:69], 0, s[22:23]
	v_lshl_add_u64 v[68:69], v[68:69], 0, v[184:185]
	v_lshlrev_b32_e32 v184, 10, v70
	v_lshl_add_u64 v[70:71], v[68:69], 0, v[184:185]
	s_waitcnt lgkmcnt(0)
	flat_store_dwordx4 v[70:71], v[64:67]
	ds_read_b128 v[64:67], v72 offset:1088
	v_or_b32_e32 v70, 0x1000, v184
	v_mov_b32_e32 v71, v185
	v_lshl_add_u64 v[70:71], v[68:69], 0, v[70:71]
	v_mfma_f32_32x32x16_bf16 v[32:47], v[144:147], v[194:197], v[32:47]
	s_waitcnt lgkmcnt(0)
	flat_store_dwordx4 v[70:71], v[64:67]
	ds_read_b128 v[64:67], v72 offset:2176
	v_or_b32_e32 v70, 0x2000, v184
	v_mov_b32_e32 v71, v185
	v_lshl_add_u64 v[70:71], v[68:69], 0, v[70:71]
	s_mul_i32 s22, s54, 0x180
	s_waitcnt lgkmcnt(0)
	flat_store_dwordx4 v[70:71], v[64:67]
	ds_read_b128 v[64:67], v72 offset:3264
	v_or_b32_e32 v70, 0x3000, v184
	v_mov_b32_e32 v71, v185
	v_lshl_add_u64 v[70:71], v[68:69], 0, v[70:71]
	v_mfma_f32_32x32x16_bf16 v[48:63], v[202:205], v[194:197], v[48:63]
	s_waitcnt lgkmcnt(0)
	flat_store_dwordx4 v[70:71], v[64:67]
	ds_read_b128 v[64:67], v72 offset:4352
	v_or_b32_e32 v70, 0x4000, v184
	v_mov_b32_e32 v71, v185
	v_lshl_add_u64 v[70:71], v[68:69], 0, v[70:71]
	v_mul_f32_e32 v75, v32, v158
	s_waitcnt lgkmcnt(0)
	flat_store_dwordx4 v[70:71], v[64:67]
	ds_read_b128 v[64:67], v72 offset:5440
	v_or_b32_e32 v70, 0x5000, v184
	v_mov_b32_e32 v71, v185
	v_lshl_add_u64 v[70:71], v[68:69], 0, v[70:71]
	v_mul_f32_e32 v76, v33, v158
	s_waitcnt lgkmcnt(0)
; DEV void epi_ukv(f32x16 (&acc)[1][8], const Params& P, int layer, int batch, int m0, int head, int wid, int r32, int hi, char* lds) {
;     ...
;   float s = 0.f;
; #pragma unroll
;   for (int ni = 0; ni < 4; ++ni)
; #pragma unroll
;     for (int r = 0; r < 16; ++r) { acc[0][ni][r] *= rc; s += acc[0][ni][r] * acc[0][ni][r]; }
;   float4 kr[2][4];
; #pragma unroll
;   for (int b = 0; b < 2; ++b)
; #pragma unroll
;     for (int r4 = 0; r4 < 4; ++r4) {
;       kr[b][r4] = *reinterpret_cast<const float4*>(WS{P.ws}.KR() + (long)t * 64 + b * 32 + r4 * 8 + hi * 4);
;       s += kr[b][r4].x * kr[b][r4].x + kr[b][r4].y * kr[b][r4].y + kr[b][r4].z * kr[b][r4].z + kr[b][r4].w * kr[b][r4].w;
;     }
;   s = swapsum(s);
;   const float inv = __builtin_amdgcn_rsqf(s * (1.f / 192.f) + EPS);
;   const float* g = WS{P.ws}.consts() + layer * 1024 + 512;
;   char* dst = slab + r32 * 400;
; #pragma unroll
;   for (int ni = 0; ni < 4; ++ni)
; #pragma unroll
;     for (int r4 = 0; r4 < 4; ++r4) {
;       const int c = ni * 32 + r4 * 8 + hi * 4;
;       const float4 gg = *reinterpret_cast<const float4*>(g + c);
	flat_store_dwordx4 v[70:71], v[64:67]
	ds_read_b128 v[64:67], v72 offset:6528
	v_or_b32_e32 v70, 0x6000, v184
	v_mov_b32_e32 v71, v185
	v_lshl_add_u64 v[70:71], v[68:69], 0, v[70:71]
	v_or_b32_e32 v184, 0x7000, v184
	s_waitcnt lgkmcnt(0)
	flat_store_dwordx4 v[70:71], v[64:67]
	ds_read_b128 v[64:67], v72 offset:7616
	v_lshl_add_u64 v[68:69], v[68:69], 0, v[184:185]
	v_lshlrev_b64 v[32:33], 8, v[150:151]
	v_lshl_add_u64 v[32:33], s[68:69], 0, v[32:33]
	v_lshlrev_b32_e32 v184, 4, v155
	s_waitcnt lgkmcnt(0)
	flat_store_dwordx4 v[68:69], v[64:67]
	s_waitcnt lgkmcnt(0)
	v_mul_f32_e32 v73, v56, v158
	v_mul_f32_e32 v74, v57, v158
	v_lshl_add_u64 v[56:57], v[32:33], 0, v[184:185]
	v_mul_f32_e32 v64, v48, v158
	v_mul_f32_e32 v65, v49, v158
	v_mul_f32_e32 v67, v50, v158
	v_mul_f32_e32 v68, v51, v158
	flat_load_dwordx4 v[48:51], v[56:57]
	v_mul_f32_e32 v83, v40, v158
	v_mul_f32_e32 v84, v41, v158
	v_mul_f32_e32 v85, v42, v158
	v_mul_f32_e32 v86, v43, v158
	flat_load_dwordx4 v[40:43], v[56:57] offset:32
	v_mul_f32_e32 v79, v36, v158
	v_mul_f32_e32 v80, v37, v158
	v_mul_f32_e32 v81, v38, v158
	v_mul_f32_e32 v82, v39, v158
	flat_load_dwordx4 v[36:39], v[56:57] offset:64
	v_mfma_f32_32x32x16_bf16 v[16:31], v[136:139], v[194:197], v[16:31]
	v_mul_f32_e32 v77, v34, v158
	v_mul_f32_e32 v78, v35, v158
	flat_load_dwordx4 v[32:35], v[56:57] offset:96
	v_mul_f32_e32 v69, v52, v158
	v_mul_f32_e32 v70, v53, v158
	v_mul_f32_e32 v71, v54, v158
	v_mul_f32_e32 v72, v55, v158
	v_mul_f32_e32 v87, v44, v158
	v_mul_f32_e32 v88, v45, v158
	v_mul_f32_e32 v89, v46, v158
	v_mul_f32_e32 v90, v47, v158
	flat_load_dwordx4 v[52:55], v[56:57] offset:128
	flat_load_dwordx4 v[44:47], v[56:57] offset:160
	v_mul_f32_e32 v91, v16, v158
	v_mul_f32_e32 v92, v17, v158
	v_mul_f32_e32 v93, v18, v158
	v_mul_f32_e32 v94, v19, v158
	v_mul_f32_e32 v95, v20, v158
	v_mul_f32_e32 v96, v21, v158
	v_mul_f32_e32 v97, v22, v158
	v_mul_f32_e32 v98, v23, v158
	flat_load_dwordx4 v[20:23], v[56:57] offset:192
	flat_load_dwordx4 v[16:19], v[56:57] offset:224
	v_mul_f32_e32 v66, v65, v65
	v_fmac_f32_e32 v66, v64, v64
	v_fmac_f32_e32 v66, v67, v67
	v_fmac_f32_e32 v66, v68, v68
	v_fmac_f32_e32 v66, v69, v69
	v_mfma_f32_32x32x16_bf16 v[0:15], v[198:201], v[194:197], v[0:15]
	v_fmac_f32_e32 v66, v70, v70
	v_fmac_f32_e32 v66, v71, v71
	v_fmac_f32_e32 v66, v72, v72
	v_fmac_f32_e32 v66, v73, v73
	v_fmac_f32_e32 v66, v74, v74
	v_mul_f32_e32 v58, v58, v158
	v_fmac_f32_e32 v66, v58, v58
	v_mul_f32_e32 v59, v59, v158
	v_fmac_f32_e32 v66, v59, v59
	v_mul_f32_e32 v60, v60, v158
	v_fmac_f32_e32 v66, v60, v60
	v_mul_f32_e32 v61, v61, v158
	v_mul_f32_e32 v101, v26, v158
	v_mul_f32_e32 v56, v27, v158
	v_lshl_add_u64 v[26:27], s[10:11], 0, v[184:185]
	v_fmac_f32_e32 v66, v61, v61
	v_mul_f32_e32 v62, v62, v158
	v_mul_f32_e32 v57, v0, v158
	v_mul_f32_e32 v102, v1, v158
	v_mul_f32_e32 v103, v2, v158
	v_mul_f32_e32 v104, v3, v158
	flat_load_dwordx4 v[0:3], v[26:27] offset:2048
	global_load_dwordx4 v[194:197], v[26:27], off offset:2080
	global_load_dwordx4 v[198:201], v[26:27], off offset:2112
	global_load_dwordx4 v[202:205], v[26:27], off offset:2144
	global_load_dwordx4 v[206:209], v[26:27], off offset:2176
	global_load_dwordx4 v[210:213], v[26:27], off offset:2208
	global_load_dwordx4 v[214:217], v[26:27], off offset:2240
	global_load_dwordx4 v[218:221], v[26:27], off offset:2272
	global_load_dwordx4 v[222:225], v[26:27], off offset:2304
	global_load_dwordx4 v[232:235], v[26:27], off offset:2336
	global_load_dwordx4 v[236:239], v[26:27], off offset:2368
	global_load_dwordx4 v[240:243], v[26:27], off offset:2400
	global_load_dwordx4 v[244:247], v[26:27], off offset:2432
	global_load_dwordx4 v[248:251], v[26:27], off offset:2464
	global_load_dwordx4 v[170:173], v[26:27], off offset:2496
	global_load_dwordx4 v[174:177], v[26:27], off offset:2528
	v_fmac_f32_e32 v66, v62, v62
	v_mul_f32_e32 v63, v63, v158
	v_fmac_f32_e32 v66, v63, v63
	v_fmac_f32_e32 v66, v75, v75
	v_fmac_f32_e32 v66, v76, v76
	v_fmac_f32_e32 v66, v77, v77
	v_fmac_f32_e32 v66, v78, v78
	v_fmac_f32_e32 v66, v79, v79
	v_fmac_f32_e32 v66, v80, v80
	v_fmac_f32_e32 v66, v81, v81
	v_fmac_f32_e32 v66, v82, v82
	v_fmac_f32_e32 v66, v83, v83
	v_fmac_f32_e32 v66, v84, v84
	v_fmac_f32_e32 v66, v85, v85
	v_fmac_f32_e32 v66, v86, v86
	v_fmac_f32_e32 v66, v87, v87
	v_fmac_f32_e32 v66, v88, v88
	v_fmac_f32_e32 v66, v89, v89
	v_fmac_f32_e32 v66, v90, v90
	v_fmac_f32_e32 v66, v91, v91
	v_fmac_f32_e32 v66, v92, v92
	v_fmac_f32_e32 v66, v93, v93
	v_fmac_f32_e32 v66, v94, v94
	v_fmac_f32_e32 v66, v95, v95
	v_fmac_f32_e32 v66, v96, v96
	v_fmac_f32_e32 v66, v97, v97
	v_fmac_f32_e32 v66, v98, v98
	v_mul_f32_e32 v99, v24, v158
	v_fmac_f32_e32 v66, v99, v99
	v_mul_f32_e32 v100, v25, v158
	v_fmac_f32_e32 v66, v100, v100
	v_fmac_f32_e32 v66, v101, v101
	v_fmac_f32_e32 v66, v56, v56
	v_mul_f32_e32 v28, v28, v158
	v_fmac_f32_e32 v66, v28, v28
	v_mul_f32_e32 v29, v29, v158
	v_fmac_f32_e32 v66, v29, v29
	v_mul_f32_e32 v30, v30, v158
	v_fmac_f32_e32 v66, v30, v30
	v_mul_f32_e32 v31, v31, v158
	v_fmac_f32_e32 v66, v31, v31
	v_fmac_f32_e32 v66, v57, v57
	v_fmac_f32_e32 v66, v102, v102
	v_fmac_f32_e32 v66, v103, v103
	v_fmac_f32_e32 v66, v104, v104
	v_mul_f32_e32 v105, v4, v158
	v_fmac_f32_e32 v66, v105, v105
	v_mul_f32_e32 v106, v5, v158
	v_fmac_f32_e32 v66, v106, v106
	v_mul_f32_e32 v107, v6, v158
	v_fmac_f32_e32 v66, v107, v107
	v_mul_f32_e32 v108, v7, v158
	v_fmac_f32_e32 v66, v108, v108
	v_mul_f32_e32 v8, v8, v158
	v_fmac_f32_e32 v66, v8, v8
	v_mul_f32_e32 v9, v9, v158
	v_fmac_f32_e32 v66, v9, v9
	v_mul_f32_e32 v10, v10, v158
	v_fmac_f32_e32 v66, v10, v10
	v_mul_f32_e32 v11, v11, v158
	v_fmac_f32_e32 v66, v11, v11
	v_mul_f32_e32 v12, v12, v158
	v_fmac_f32_e32 v66, v12, v12
	v_mul_f32_e32 v13, v13, v158
	s_waitcnt vmcnt(0) lgkmcnt(0)
; DEV void epi_ukv(f32x16 (&acc)[1][8], const Params& P, int layer, int batch, int m0, int head, int wid, int r32, int hi, char* lds) {
;     ...
;   float4 kr[2][4];
; #pragma unroll
;   for (int b = 0; b < 2; ++b)
; #pragma unroll
;     for (int r4 = 0; r4 < 4; ++r4) {
;       kr[b][r4] = *reinterpret_cast<const float4*>(WS{P.ws}.KR() + (long)t * 64 + b * 32 + r4 * 8 + hi * 4);
;       s += kr[b][r4].x * kr[b][r4].x + kr[b][r4].y * kr[b][r4].y + kr[b][r4].z * kr[b][r4].z + kr[b][r4].w * kr[b][r4].w;
;     }
;   s = swapsum(s);
;   const float inv = __builtin_amdgcn_rsqf(s * (1.f / 192.f) + EPS);
;   const float* g = WS{P.ws}.consts() + layer * 1024 + 512;
;   char* dst = slab + r32 * 400;
; #pragma unroll
;   for (int ni = 0; ni < 4; ++ni)
; #pragma unroll
;     for (int r4 = 0; r4 < 4; ++r4) {
;       const int c = ni * 32 + r4 * 8 + hi * 4;
;       const float4 gg = *reinterpret_cast<const float4*>(g + c);
;       const f32x16& a = acc[0][ni];
;       st4lds(dst, c, a[r4 * 4] * inv * gg.x, a[r4 * 4 + 1] * inv * gg.y, a[r4 * 4 + 2] * inv * gg.z, a[r4 * 4 + 3] * inv * gg.w);
;     }
	v_mul_f32_e32 v4, v49, v49
	v_fmac_f32_e32 v66, v13, v13
	v_mul_f32_e32 v14, v14, v158
	v_fmac_f32_e32 v4, v48, v48
	v_mul_f32_e32 v5, v41, v41
	v_fmac_f32_e32 v66, v14, v14
	v_mul_f32_e32 v15, v15, v158
	v_fmac_f32_e32 v4, v50, v50
	v_fmac_f32_e32 v5, v40, v40
	v_fmac_f32_e32 v66, v15, v15
	v_fmac_f32_e32 v4, v51, v51
	v_fmac_f32_e32 v5, v42, v42
	v_add_f32_e32 v4, v66, v4
	v_fmac_f32_e32 v5, v43, v43
	v_add_f32_e32 v4, v4, v5
	v_mul_f32_e32 v5, v37, v37
	v_fmac_f32_e32 v5, v36, v36
	v_fmac_f32_e32 v5, v38, v38
	v_fmac_f32_e32 v5, v39, v39
	v_add_f32_e32 v4, v4, v5
	v_mul_f32_e32 v5, v33, v33
	v_fmac_f32_e32 v5, v32, v32
	v_fmac_f32_e32 v5, v34, v34
	v_fmac_f32_e32 v5, v35, v35
	v_mov_b32_e32 v6, v53
	v_mov_b32_e32 v7, v45
	v_add_f32_e32 v24, v4, v5
	v_mov_b32_e32 v4, v52
	v_mov_b32_e32 v5, v44
	v_pk_mul_f32 v[6:7], v[6:7], v[6:7]
	v_lshlrev_b32_e32 v184, 5, v155
	v_pk_fma_f32 v[4:5], v[4:5], v[4:5], v[6:7]
	v_mov_b32_e32 v6, v54
	v_mov_b32_e32 v7, v46
	v_pk_fma_f32 v[4:5], v[6:7], v[6:7], v[4:5]
	v_mov_b32_e32 v6, v55
	v_mov_b32_e32 v7, v47
	v_pk_fma_f32 v[4:5], v[6:7], v[6:7], v[4:5]
	v_mov_b32_e32 v6, v21
	v_add_f32_e32 v4, v24, v4
	v_mov_b32_e32 v7, v17
	v_add_f32_e32 v24, v4, v5
	v_mov_b32_e32 v4, v20
	v_mov_b32_e32 v5, v16
	v_pk_mul_f32 v[6:7], v[6:7], v[6:7]
	s_nop 0
	v_pk_fma_f32 v[4:5], v[4:5], v[4:5], v[6:7]
	v_mov_b32_e32 v6, v22
	v_mov_b32_e32 v7, v18
	v_pk_fma_f32 v[4:5], v[6:7], v[6:7], v[4:5]
	v_mov_b32_e32 v6, v23
	v_mov_b32_e32 v7, v19
	v_pk_fma_f32 v[4:5], v[6:7], v[6:7], v[4:5]
	s_nop 0
	v_add_f32_e32 v4, v24, v4
	v_add_f32_e32 v4, v4, v5
	v_mov_b32_e32 v5, v4
	s_nop 1
	v_permlane32_swap_b32_e32 v4, v5
	v_add_f32_e32 v4, v4, v5
	v_fmamk_f32 v4, v4, 0x3baaaaab, v227
	v_rsq_f32_e32 v24, v4
	v_mul_u32_u24_e32 v4, 0x190, v154
	v_add3_u32 v25, v153, v4, v157
	v_mul_f32_e32 v5, v64, v24
	v_mul_f32_e32 v0, v0, v5
	v_mul_f32_e32 v5, v65, v24
	v_mul_f32_e32 v1, v1, v5
	v_mul_f32_e32 v5, v67, v24
	v_mul_f32_e32 v2, v2, v5
	v_mul_f32_e32 v5, v68, v24
	v_mul_f32_e32 v3, v3, v5
	v_cvt_pk_bf16_f32 v0, v0, v1
	v_cvt_pk_bf16_f32 v1, v2, v3
	ds_write_b64 v25, v[0:1]
	v_mul_f32_e32 v4, v69, v24
	v_mul_f32_e32 v5, v74, v24
	v_mul_f32_e32 v6, v62, v24
	v_mul_f32_e32 v7, v63, v24
	v_mul_f32_e32 v0, v4, v194
	v_mul_f32_e32 v4, v70, v24
	v_mul_f32_e32 v1, v4, v195
	v_mul_f32_e32 v4, v71, v24
	v_mul_f32_e32 v2, v4, v196
	v_mul_f32_e32 v4, v72, v24
	v_mul_f32_e32 v3, v4, v197
	v_cvt_pk_bf16_f32 v0, v0, v1
	v_cvt_pk_bf16_f32 v1, v2, v3
	ds_write_b64 v25, v[0:1] offset:16
	v_mul_f32_e32 v4, v73, v24
	v_mul_f32_e32 v0, v4, v198
	v_mul_f32_e32 v4, v58, v24
	v_mul_f32_e32 v1, v5, v199
	v_mul_f32_e32 v2, v4, v200
	v_mul_f32_e32 v4, v59, v24
	v_mul_f32_e32 v3, v4, v201
	v_cvt_pk_bf16_f32 v0, v0, v1
	v_cvt_pk_bf16_f32 v1, v2, v3
	ds_write_b64 v25, v[0:1] offset:32
	v_mul_f32_e32 v4, v60, v24
	v_mul_f32_e32 v5, v61, v24
	v_mul_f32_e32 v0, v4, v202
	v_mul_f32_e32 v1, v5, v203
	v_mul_f32_e32 v2, v6, v204
	v_mul_f32_e32 v3, v7, v205
	v_cvt_pk_bf16_f32 v0, v0, v1
	v_cvt_pk_bf16_f32 v1, v2, v3
	ds_write_b64 v25, v[0:1] offset:48
	v_mul_f32_e32 v4, v75, v24
	v_mul_f32_e32 v5, v76, v24
	v_mul_f32_e32 v6, v77, v24
	v_mul_f32_e32 v7, v78, v24
	v_mul_f32_e32 v0, v4, v206
	v_mul_f32_e32 v1, v5, v207
	v_mul_f32_e32 v2, v6, v208
	v_mul_f32_e32 v3, v7, v209
	v_cvt_pk_bf16_f32 v0, v0, v1
	v_cvt_pk_bf16_f32 v1, v2, v3
	ds_write_b64 v25, v[0:1] offset:64
	v_mul_f32_e32 v4, v79, v24
	v_mul_f32_e32 v5, v80, v24
	v_mul_f32_e32 v6, v81, v24
	v_mul_f32_e32 v7, v82, v24
	v_mul_f32_e32 v0, v4, v210
	v_mul_f32_e32 v1, v5, v211
	v_mul_f32_e32 v2, v6, v212
	v_mul_f32_e32 v3, v7, v213
	v_cvt_pk_bf16_f32 v0, v0, v1
	v_cvt_pk_bf16_f32 v1, v2, v3
	ds_write_b64 v25, v[0:1] offset:80
	v_mul_f32_e32 v4, v83, v24
	v_mul_f32_e32 v5, v84, v24
	v_mul_f32_e32 v6, v85, v24
	v_mul_f32_e32 v7, v86, v24
	v_mul_f32_e32 v0, v4, v214
	v_mul_f32_e32 v1, v5, v215
	v_mul_f32_e32 v2, v6, v216
	v_mul_f32_e32 v3, v7, v217
	v_cvt_pk_bf16_f32 v0, v0, v1
	v_cvt_pk_bf16_f32 v1, v2, v3
	ds_write_b64 v25, v[0:1] offset:96
	v_mul_f32_e32 v4, v87, v24
	v_mul_f32_e32 v5, v88, v24
	v_mul_f32_e32 v6, v89, v24
	v_mul_f32_e32 v7, v90, v24
	v_mul_f32_e32 v0, v4, v218
	v_mul_f32_e32 v1, v5, v219
	v_mul_f32_e32 v2, v6, v220
	v_mul_f32_e32 v3, v7, v221
	v_cvt_pk_bf16_f32 v0, v0, v1
	v_cvt_pk_bf16_f32 v1, v2, v3
	ds_write_b64 v25, v[0:1] offset:112
	v_mul_f32_e32 v4, v91, v24
	v_mul_f32_e32 v5, v92, v24
	v_mul_f32_e32 v6, v93, v24
	v_mul_f32_e32 v7, v94, v24
	v_mul_f32_e32 v0, v4, v222
	v_mul_f32_e32 v1, v5, v223
	v_mul_f32_e32 v2, v6, v224
	v_mul_f32_e32 v3, v7, v225
	v_cvt_pk_bf16_f32 v0, v0, v1
	v_cvt_pk_bf16_f32 v1, v2, v3
	ds_write_b64 v25, v[0:1] offset:128
	v_mul_f32_e32 v4, v95, v24
	v_mul_f32_e32 v5, v96, v24
	v_mul_f32_e32 v6, v97, v24
	v_mul_f32_e32 v7, v98, v24
	v_mul_f32_e32 v0, v4, v232
	v_mul_f32_e32 v1, v5, v233
	v_mul_f32_e32 v2, v6, v234
	v_mul_f32_e32 v3, v7, v235
	v_cvt_pk_bf16_f32 v0, v0, v1
	v_cvt_pk_bf16_f32 v1, v2, v3
	ds_write_b64 v25, v[0:1] offset:144
	v_mul_f32_e32 v4, v99, v24
	v_mul_f32_e32 v5, v100, v24
	v_mul_f32_e32 v6, v101, v24
	v_mul_f32_e32 v7, v56, v24
	v_mul_f32_e32 v0, v4, v236
	v_mul_f32_e32 v1, v5, v237
	v_mul_f32_e32 v2, v6, v238
	v_mul_f32_e32 v3, v7, v239
	v_cvt_pk_bf16_f32 v0, v0, v1
	v_cvt_pk_bf16_f32 v1, v2, v3
	ds_write_b64 v25, v[0:1] offset:160
	v_mul_f32_e32 v4, v28, v24
	v_mul_f32_e32 v5, v29, v24
	v_mul_f32_e32 v6, v30, v24
	v_mul_f32_e32 v7, v31, v24
	v_mov_b32_e32 v30, v48
	v_mov_b32_e32 v31, v52
	v_mov_b32_e32 v52, v49
	v_mov_b32_e32 v48, v50
	v_mov_b32_e32 v49, v54
	v_mov_b32_e32 v54, v51
	v_pk_mul_f32 v[30:31], v[30:31], v[24:25] op_sel_hi:[1,0]
; DEV void epi_ukv(f32x16 (&acc)[1][8], const Params& P, int layer, int batch, int m0, int head, int wid, int r32, int hi, char* lds) {
;     ...
; #pragma unroll
;   for (int ni = 0; ni < 4; ++ni)
; #pragma unroll
;     for (int r4 = 0; r4 < 4; ++r4) {
;       const int c = ni * 32 + r4 * 8 + hi * 4;
;       const float4 gg = *reinterpret_cast<const float4*>(g + c);
;       const f32x16& a = acc[0][ni];
;       st4lds(dst, c, a[r4 * 4] * inv * gg.x, a[r4 * 4 + 1] * inv * gg.y, a[r4 * 4 + 2] * inv * gg.z, a[r4 * 4 + 3] * inv * gg.w);
;     }
;   const int pos = batch ? t : (t & 4095);
;   const float2* rp = WS{P.ws}.rope() + (long)pos * 32;
; #pragma unroll
;   for (int r4 = 0; r4 < 4; ++r4) {
;     const int i = r4 * 8 + hi * 4;
;     const float4 g1 = *reinterpret_cast<const float4*>(g + 128 + i), g2 = *reinterpret_cast<const float4*>(g + 160 + i);
;     const float4 cs01 = *reinterpret_cast<const float4*>(rp + i), cs23 = *reinterpret_cast<const float4*>(rp + i + 2);
;     const float x1[4] = {kr[0][r4].x * inv * g1.x, kr[0][r4].y * inv * g1.y, kr[0][r4].z * inv * g1.z, kr[0][r4].w * inv * g1.w};
;     const float x2[4] = {kr[1][r4].x * inv * g2.x, kr[1][r4].y * inv * g2.y, kr[1][r4].z * inv * g2.z, kr[1][r4].w * inv * g2.w};
;     const float cc[4] = {cs01.x, cs01.z, cs23.x, cs23.z}, sn[4] = {cs01.y, cs01.w, cs23.y, cs23.w};
;     st4lds(dst, 128 + i, x1[0] * cc[0] - x2[0] * sn[0], x1[1] * cc[1] - x2[1] * sn[1], x1[2] * cc[2] - x2[2] * sn[2], x1[3] * cc[3] - x2[3] * sn[3]);
;     st4lds(dst, 160 + i, x1[0] * sn[0] + x2[0] * cc[0], x1[1] * sn[1] + x2[1] * cc[1], x1[2] * sn[2] + x2[2] * cc[2], x1[3] * sn[3] + x2[3] * cc[3]);
	v_pk_mul_f32 v[50:51], v[52:53], v[24:25] op_sel_hi:[1,0]
	v_pk_mul_f32 v[48:49], v[48:49], v[24:25] op_sel_hi:[1,0]
	v_pk_mul_f32 v[52:53], v[54:55], v[24:25] op_sel_hi:[1,0]
	v_mul_f32_e32 v0, v4, v240
	v_mul_f32_e32 v1, v5, v241
	v_mul_f32_e32 v2, v6, v242
	v_mul_f32_e32 v3, v7, v243
	v_cvt_pk_bf16_f32 v0, v0, v1
	v_cvt_pk_bf16_f32 v1, v2, v3
	ds_write_b64 v25, v[0:1] offset:176
	v_mul_f32_e32 v4, v57, v24
	v_mul_f32_e32 v5, v102, v24
	v_mul_f32_e32 v6, v103, v24
	v_mul_f32_e32 v7, v104, v24
	v_mul_f32_e32 v0, v4, v244
	v_mul_f32_e32 v1, v5, v245
	v_mul_f32_e32 v2, v6, v246
	v_mul_f32_e32 v3, v7, v247
	v_cvt_pk_bf16_f32 v0, v0, v1
	v_cvt_pk_bf16_f32 v1, v2, v3
	ds_write_b64 v25, v[0:1] offset:192
	v_mul_f32_e32 v4, v105, v24
	v_mul_f32_e32 v5, v106, v24
	v_mul_f32_e32 v6, v107, v24
	v_mul_f32_e32 v7, v108, v24
	v_mul_f32_e32 v0, v4, v248
	v_mul_f32_e32 v1, v5, v249
	v_mul_f32_e32 v2, v6, v250
	v_mul_f32_e32 v3, v7, v251
	v_cvt_pk_bf16_f32 v0, v0, v1
	v_cvt_pk_bf16_f32 v1, v2, v3
	ds_write_b64 v25, v[0:1] offset:208
	v_mul_f32_e32 v4, v8, v24
	v_mul_f32_e32 v5, v9, v24
	v_mul_f32_e32 v6, v10, v24
	v_mul_f32_e32 v7, v11, v24
	v_bitop3_b32 v8, v148, s2, v154 bitop3:0xc8
	v_cndmask_b32_e64 v8, v150, v8, s[26:27]
	v_ashrrev_i32_e32 v9, 31, v8
	v_lshlrev_b64 v[8:9], 8, v[8:9]
	v_lshl_add_u64 v[8:9], s[12:13], 0, v[8:9]
	v_lshl_add_u64 v[28:29], v[8:9], 0, v[184:185]
	v_mul_f32_e32 v0, v4, v170
	v_mul_f32_e32 v1, v5, v171
	v_mul_f32_e32 v2, v6, v172
	v_mul_f32_e32 v3, v7, v173
	v_cvt_pk_bf16_f32 v0, v0, v1
	v_cvt_pk_bf16_f32 v1, v2, v3
	ds_write_b64 v25, v[0:1] offset:224
	v_mul_f32_e32 v4, v12, v24
	v_mul_f32_e32 v5, v13, v24
	v_mul_f32_e32 v6, v14, v24
	v_mul_f32_e32 v7, v15, v24
	v_mul_f32_e32 v0, v4, v174
	v_mul_f32_e32 v1, v5, v175
	v_mul_f32_e32 v2, v6, v176
	v_mul_f32_e32 v3, v7, v177
	v_cvt_pk_bf16_f32 v0, v0, v1
	v_cvt_pk_bf16_f32 v1, v2, v3
	ds_write_b64 v25, v[0:1] offset:240
	flat_load_dwordx4 v[0:3], v[26:27] offset:2560
	flat_load_dwordx4 v[4:7], v[26:27] offset:2688
	flat_load_dwordx4 v[8:11], v[28:29]
	flat_load_dwordx4 v[12:15], v[28:29] offset:16
	s_waitcnt vmcnt(0) lgkmcnt(0)
	v_mov_b32_e32 v54, v0
	v_mov_b32_e32 v55, v4
	v_mov_b32_e32 v4, v1
	v_mov_b32_e32 v0, v2
	v_mov_b32_e32 v1, v6
	v_mov_b32_e32 v6, v3
	v_pk_mul_f32 v[2:3], v[30:31], v[54:55]
	v_pk_mul_f32 v[4:5], v[50:51], v[4:5]
	v_pk_mul_f32 v[0:1], v[48:49], v[0:1]
	v_pk_mul_f32 v[6:7], v[52:53], v[6:7]
	v_pk_mul_f32 v[30:31], v[2:3], v[8:9]
	v_pk_mul_f32 v[48:49], v[4:5], v[10:11]
	v_pk_mul_f32 v[50:51], v[0:1], v[12:13]
	v_pk_mul_f32 v[52:53], v[6:7], v[14:15]
	v_pk_mul_f32 v[2:3], v[2:3], v[8:9] op_sel:[1,0] op_sel_hi:[0,1]
	v_pk_mul_f32 v[4:5], v[4:5], v[10:11] op_sel:[1,0] op_sel_hi:[0,1]
	v_pk_mul_f32 v[0:1], v[0:1], v[12:13] op_sel:[1,0] op_sel_hi:[0,1]
	v_pk_mul_f32 v[6:7], v[6:7], v[14:15] op_sel:[1,0] op_sel_hi:[0,1]
	v_sub_f32_e32 v8, v30, v31
	v_sub_f32_e32 v9, v48, v49
	v_sub_f32_e32 v10, v50, v51
	v_sub_f32_e32 v11, v52, v53
	v_add_f32_e32 v2, v2, v3
	v_add_f32_e32 v3, v4, v5
	v_add_f32_e32 v4, v0, v1
	v_cvt_pk_bf16_f32 v0, v8, v9
	v_cvt_pk_bf16_f32 v1, v10, v11
	v_add_f32_e32 v5, v6, v7
	ds_write_b64 v25, v[0:1] offset:256
	v_cvt_pk_bf16_f32 v0, v2, v3
	v_cvt_pk_bf16_f32 v1, v4, v5
	ds_write_b64 v25, v[0:1] offset:320
	flat_load_dwordx4 v[0:3], v[26:27] offset:2592
	flat_load_dwordx4 v[4:7], v[26:27] offset:2720
	flat_load_dwordx4 v[8:11], v[28:29] offset:64
	flat_load_dwordx4 v[12:15], v[28:29] offset:80
	v_mov_b32_e32 v30, v40
	v_mov_b32_e32 v31, v44
	v_mov_b32_e32 v44, v41
	v_mov_b32_e32 v40, v42
	v_mov_b32_e32 v41, v46
	v_mov_b32_e32 v46, v43
	v_pk_mul_f32 v[30:31], v[30:31], v[24:25] op_sel_hi:[1,0]
	v_pk_mul_f32 v[42:43], v[44:45], v[24:25] op_sel_hi:[1,0]
	v_pk_mul_f32 v[40:41], v[40:41], v[24:25] op_sel_hi:[1,0]
	v_pk_mul_f32 v[44:45], v[46:47], v[24:25] op_sel_hi:[1,0]
	s_waitcnt vmcnt(0) lgkmcnt(0)
	v_mov_b32_e32 v46, v0
	v_mov_b32_e32 v47, v4
	v_mov_b32_e32 v4, v1
	v_mov_b32_e32 v0, v2
	v_mov_b32_e32 v1, v6
	v_mov_b32_e32 v6, v3
	v_pk_mul_f32 v[2:3], v[30:31], v[46:47]
	v_pk_mul_f32 v[4:5], v[42:43], v[4:5]
	v_pk_mul_f32 v[0:1], v[40:41], v[0:1]
	v_pk_mul_f32 v[6:7], v[44:45], v[6:7]
	v_pk_mul_f32 v[30:31], v[2:3], v[8:9]
	v_pk_mul_f32 v[40:41], v[4:5], v[10:11]
	v_pk_mul_f32 v[42:43], v[0:1], v[12:13]
	v_pk_mul_f32 v[44:45], v[6:7], v[14:15]
	v_pk_mul_f32 v[2:3], v[2:3], v[8:9] op_sel:[1,0] op_sel_hi:[0,1]
	v_pk_mul_f32 v[4:5], v[4:5], v[10:11] op_sel:[1,0] op_sel_hi:[0,1]
	v_pk_mul_f32 v[0:1], v[0:1], v[12:13] op_sel:[1,0] op_sel_hi:[0,1]
	v_pk_mul_f32 v[6:7], v[6:7], v[14:15] op_sel:[1,0] op_sel_hi:[0,1]
	v_sub_f32_e32 v8, v30, v31
	v_sub_f32_e32 v9, v40, v41
	v_sub_f32_e32 v10, v42, v43
	v_sub_f32_e32 v11, v44, v45
	v_add_f32_e32 v2, v2, v3
	v_add_f32_e32 v3, v4, v5
	v_add_f32_e32 v4, v0, v1
	v_cvt_pk_bf16_f32 v0, v8, v9
	v_cvt_pk_bf16_f32 v1, v10, v11
	v_add_f32_e32 v5, v6, v7
	ds_write_b64 v25, v[0:1] offset:272
	v_cvt_pk_bf16_f32 v0, v2, v3
	v_cvt_pk_bf16_f32 v1, v4, v5
	ds_write_b64 v25, v[0:1] offset:336
	flat_load_dwordx4 v[8:11], v[26:27] offset:2624
	flat_load_dwordx4 v[4:7], v[26:27] offset:2752
	flat_load_dwordx4 v[0:3], v[28:29] offset:128
	flat_load_dwordx4 v[12:15], v[28:29] offset:144
	v_and_b32_e32 v40, 63, v152
	v_mul_lo_u16_e32 v41, 43, v40
	v_or_b32_e32 v42, 64, v40
	v_or_b32_e32 v43, 0x80, v40
	v_lshrrev_b16_e32 v41, 10, v41
	v_mul_lo_u16_e32 v53, 43, v42
	v_mul_lo_u16_e32 v54, 0xab, v43
	v_or_b32_e32 v44, 0xc0, v40
	v_or_b32_e32 v45, 0x100, v40
	v_or_b32_e32 v46, 0x180, v40
	v_or_b32_e32 v47, 0x140, v40
	v_or_b32_e32 v48, 0x200, v40
	v_or_b32_e32 v49, 0x1c0, v40
	v_or_b32_e32 v50, 0x280, v40
	v_or_b32_e32 v51, 0x240, v40
; DEV void epi_ukv(f32x16 (&acc)[1][8], const Params& P, int layer, int batch, int m0, int head, int wid, int r32, int hi, char* lds) {
;     ...
;   const int pos = batch ? t : (t & 4095);
;   const float2* rp = WS{P.ws}.rope() + (long)pos * 32;
; #pragma unroll
;   for (int r4 = 0; r4 < 4; ++r4) {
;     const int i = r4 * 8 + hi * 4;
;     const float4 g1 = *reinterpret_cast<const float4*>(g + 128 + i), g2 = *reinterpret_cast<const float4*>(g + 160 + i);
;     const float4 cs01 = *reinterpret_cast<const float4*>(rp + i), cs23 = *reinterpret_cast<const float4*>(rp + i + 2);
;     const float x1[4] = {kr[0][r4].x * inv * g1.x, kr[0][r4].y * inv * g1.y, kr[0][r4].z * inv * g1.z, kr[0][r4].w * inv * g1.w};
;     const float x2[4] = {kr[1][r4].x * inv * g2.x, kr[1][r4].y * inv * g2.y, kr[1][r4].z * inv * g2.z, kr[1][r4].w * inv * g2.w};
;     const float cc[4] = {cs01.x, cs01.z, cs23.x, cs23.z}, sn[4] = {cs01.y, cs01.w, cs23.y, cs23.w};
;     st4lds(dst, 128 + i, x1[0] * cc[0] - x2[0] * sn[0], x1[1] * cc[1] - x2[1] * sn[1], x1[2] * cc[2] - x2[2] * sn[2], x1[3] * cc[3] - x2[3] * sn[3]);
;     st4lds(dst, 160 + i, x1[0] * sn[0] + x2[0] * cc[0], x1[1] * sn[1] + x2[1] * cc[1], x1[2] * sn[2] + x2[2] * cc[2], x1[3] * sn[3] + x2[3] * cc[3]);
;   }
;   slab_flush<24, 400>(slab, WS{P.ws}.KB() + (long)(m0 + wid * 32) * 768 + head * 192, 768, hi * 32 + r32);
	v_or_b32_e32 v52, 0x2c0, v40
	v_mad_i32_i24 v40, v41, s58, v40
	v_mul_u32_u24_e32 v64, 0x190, v41
	v_mul_u32_u24_e32 v65, 0x300, v41
	v_lshrrev_b16_e32 v41, 10, v53
	v_lshrrev_b16_e32 v53, 12, v54
	v_mad_i32_i24 v69, v41, s58, v42
	v_mad_i32_i24 v72, v53, s58, v43
	v_mov_b32_e32 v42, v36
	v_mov_b32_e32 v43, v20
	v_mov_b32_e32 v20, v37
	v_mov_b32_e32 v36, v38
	v_mov_b32_e32 v37, v22
	v_mov_b32_e32 v22, v39
	v_pk_mul_f32 v[38:39], v[42:43], v[24:25] op_sel_hi:[1,0]
	v_pk_mul_f32 v[20:21], v[20:21], v[24:25] op_sel_hi:[1,0]
	v_pk_mul_f32 v[36:37], v[36:37], v[24:25] op_sel_hi:[1,0]
	v_pk_mul_f32 v[22:23], v[22:23], v[24:25] op_sel_hi:[1,0]
	v_mul_lo_u16_e32 v55, 0xab, v44
	v_mul_u32_u24_e32 v56, 0xaab, v45
	v_mul_u32_u24_e32 v57, 0xaab, v47
	v_mul_u32_u24_e32 v58, 0xaab, v46
	v_mul_u32_u24_e32 v59, 0xaab, v49
	v_mul_u32_u24_e32 v60, 0xaab, v48
	v_mul_u32_u24_e32 v61, 0xaab, v51
	v_mul_u32_u24_e32 v62, 0xaab, v50
	v_mov_b64_e32 v[30:31], s[70:71]
	v_mul_u32_u24_e32 v63, 0xaab, v52
	v_lshrrev_b16_e32 v54, 12, v55
	v_lshrrev_b32_e32 v55, 16, v56
	v_lshrrev_b32_e32 v56, 16, v57
	v_lshrrev_b32_e32 v66, 16, v58
	v_perm_b32 v57, v58, v57, s44
	v_lshrrev_b32_e32 v58, 16, v59
	v_lshrrev_b32_e32 v67, 16, v60
	v_perm_b32 v59, v60, v59, s44
	v_lshrrev_b32_e32 v60, 16, v61
	v_lshrrev_b32_e32 v68, 16, v62
	v_mad_i64_i32 v[30:31], s[2:3], v148, s39, v[30:31]
	v_perm_b32 v61, v62, v61, s44
	v_lshrrev_b32_e32 v62, 16, v63
	v_lshlrev_b32_e32 v63, 4, v40
	v_mad_i32_i24 v48, v67, s58, v48
	v_mad_i32_i24 v51, v60, s58, v51
	v_mad_i32_i24 v50, v68, s58, v50
	v_mad_i32_i24 v52, v62, s58, v52
	v_lshlrev_b32_e32 v75, 4, v48
	v_lshlrev_b32_e32 v77, 4, v51
	v_lshlrev_b32_e32 v78, 4, v50
	v_lshlrev_b32_e32 v40, 3, v40
	v_lshlrev_b32_e32 v184, 1, v65
	v_mul_u32_u24_e32 v70, 0x190, v41
	v_mul_u32_u24_e32 v71, 0x300, v41
	v_ashrrev_i32_e32 v41, 31, v40
	v_lshlrev_b32_e32 v79, 4, v52
	s_waitcnt vmcnt(0) lgkmcnt(0)
	v_mov_b32_e32 v42, v8
	v_mov_b32_e32 v43, v4
	v_mov_b32_e32 v4, v9
	v_mov_b32_e32 v8, v10
	v_mov_b32_e32 v9, v6
	v_mov_b32_e32 v6, v11
	v_pk_mul_f32 v[10:11], v[38:39], v[42:43]
	v_pk_mul_f32 v[4:5], v[20:21], v[4:5]
	v_pk_mul_f32 v[8:9], v[36:37], v[8:9]
	v_pk_mul_f32 v[6:7], v[22:23], v[6:7]
	v_pk_mul_f32 v[20:21], v[10:11], v[0:1]
	v_pk_mul_f32 v[22:23], v[4:5], v[2:3]
	v_pk_mul_f32 v[36:37], v[8:9], v[12:13]
	v_pk_mul_f32 v[38:39], v[6:7], v[14:15]
	v_pk_mul_f32 v[0:1], v[10:11], v[0:1] op_sel:[1,0] op_sel_hi:[0,1]
	v_pk_mul_f32 v[2:3], v[4:5], v[2:3] op_sel:[1,0] op_sel_hi:[0,1]
	v_pk_mul_f32 v[4:5], v[8:9], v[12:13] op_sel:[1,0] op_sel_hi:[0,1]
	v_pk_mul_f32 v[6:7], v[6:7], v[14:15] op_sel:[1,0] op_sel_hi:[0,1]
	v_sub_f32_e32 v8, v20, v21
	v_sub_f32_e32 v9, v22, v23
	v_sub_f32_e32 v10, v36, v37
	v_sub_f32_e32 v11, v38, v39
	v_add_f32_e32 v12, v0, v1
	v_cvt_pk_bf16_f32 v0, v8, v9
	v_cvt_pk_bf16_f32 v1, v10, v11
	v_add_f32_e32 v2, v2, v3
	v_add_f32_e32 v3, v4, v5
	v_add_f32_e32 v4, v6, v7
	ds_write_b64 v25, v[0:1] offset:288
	v_cvt_pk_bf16_f32 v0, v12, v2
	v_cvt_pk_bf16_f32 v1, v3, v4
	ds_write_b64 v25, v[0:1] offset:352
	flat_load_dwordx4 v[0:3], v[26:27] offset:2656
	flat_load_dwordx4 v[4:7], v[26:27] offset:2784
	flat_load_dwordx4 v[8:11], v[28:29] offset:192
	flat_load_dwordx4 v[12:15], v[28:29] offset:208
	v_mad_i32_i24 v23, v54, s58, v44
	v_mad_i32_i24 v36, v55, s58, v45
	v_mad_i32_i24 v38, v56, s58, v47
	v_mad_i32_i24 v42, v66, s58, v46
	v_mad_i32_i24 v44, v58, s58, v49
	v_pk_mul_lo_u16 v46, v59, s37 op_sel_hi:[1,0]
	v_mul_u32_u24_e32 v39, 0x190, v55
	v_mul_u32_u24_e32 v45, 0x300, v55
	v_pk_mul_lo_u16 v29, v57, s37 op_sel_hi:[1,0]
	v_mul_u32_u24_e32 v47, 0x300, v56
	v_mul_u32_u24_e32 v55, 0x300, v67
	v_pk_mul_lo_u16 v56, v61, s37 op_sel_hi:[1,0]
	v_mul_u32_u24_e32 v57, 0x300, v60
	v_mul_u32_u24_e32 v59, 0x190, v62
	v_mul_u32_u24_e32 v60, 0x300, v62
	v_lshl_add_u64 v[20:21], v[30:31], 0, s[22:23]
	v_add3_u32 v61, v153, v64, v63
	v_lshlrev_b32_e32 v31, 4, v69
	v_lshlrev_b32_e32 v22, 3, v69
	v_lshlrev_b32_e32 v62, 4, v72
	v_lshlrev_b32_e32 v26, 3, v72
	v_lshlrev_b32_e32 v64, 4, v36
	v_lshlrev_b32_e32 v30, 3, v36
	v_lshlrev_b32_e32 v67, 4, v38
	v_lshlrev_b32_e32 v36, 3, v38
	v_lshlrev_b32_e32 v69, 4, v42
	v_lshlrev_b32_e32 v38, 3, v42
	v_and_b32_e32 v72, 0xfff0, v46
	v_lshlrev_b32_e32 v73, 4, v44
	v_lshlrev_b32_e32 v42, 3, v44
	v_lshrrev_b32_e32 v74, 16, v46
	v_lshlrev_b32_e32 v44, 3, v48
	v_lshlrev_b32_e32 v46, 3, v51
	v_lshlrev_b32_e32 v48, 3, v50
	v_mov_b32_e32 v50, v32
	v_mov_b32_e32 v51, v16
	v_mov_b32_e32 v16, v33
	v_mov_b32_e32 v32, v34
	v_mov_b32_e32 v33, v18
	v_mov_b32_e32 v18, v35
	v_pk_mul_f32 v[34:35], v[50:51], v[24:25] op_sel_hi:[1,0]
	v_pk_mul_f32 v[16:17], v[16:17], v[24:25] op_sel_hi:[1,0]
	v_pk_mul_f32 v[32:33], v[32:33], v[24:25] op_sel_hi:[1,0]
	v_pk_mul_f32 v[18:19], v[18:19], v[24:25] op_sel_hi:[1,0]
	v_add3_u32 v70, v153, v70, v31
	v_lshlrev_b32_e32 v63, 4, v23
	v_lshlrev_b32_e32 v28, 3, v23
	v_ashrrev_i32_e32 v23, 31, v22
	v_mul_u32_u24_e32 v27, 0x190, v53
	v_add3_u32 v62, v153, v27, v62
	v_mul_u32_u24_e32 v43, 0x300, v53
	v_ashrrev_i32_e32 v27, 31, v26
	v_mul_u32_u24_e32 v37, 0x190, v54
	v_add3_u32 v63, v153, v37, v63
	v_mul_u32_u24_e32 v53, 0x300, v54
	v_mul_u32_u24_e32 v54, 0x300, v66
	v_mul_u32_u24_e32 v49, 0x300, v58
	v_mul_u32_u24_e32 v58, 0x300, v68
	v_and_b32_e32 v66, 0xfff0, v29
	v_lshrrev_b32_e32 v68, 16, v29
	v_ashrrev_i32_e32 v29, 31, v28
	v_add3_u32 v64, v153, v39, v64
	v_ashrrev_i32_e32 v31, 31, v30
	v_add3_u32 v66, v153, v66, v67
	v_ashrrev_i32_e32 v37, 31, v36
	v_ashrrev_i32_e32 v39, 31, v38
	v_and_b32_e32 v76, 0xfff0, v56
	v_lshrrev_b32_e32 v56, 16, v56
	s_waitcnt vmcnt(0) lgkmcnt(0)
; #define LDSP(T) __attribute__((address_space(3))) T*
; template <int NCH, int STRIDE> DEV void slab_flush(char* slab, u16* grow0, int gstride, int lane) {
;   asm volatile("s_waitcnt lgkmcnt(0)" ::: "memory");
; #pragma unroll
;   for (int i = 0; i < NCH / 2; ++i) {
;     const int q = i * 64 + lane, row = q / NCH, cc = q - row * NCH;
;     const u32x4 v = *(LDSP(const u32x4))(slab + row * STRIDE + cc * 16);
;     *reinterpret_cast<u32x4*>(grow0 + (long)row * gstride + cc * 8) = v;
;   }
;   asm volatile("s_waitcnt lgkmcnt(0)" ::: "memory");
; }
; DEV void epi_ukv(f32x16 (&acc)[1][8], const Params& P, int layer, int batch, int m0, int head, int wid, int r32, int hi, char* lds) {
;     ...
;   const int pos = batch ? t : (t & 4095);
;   const float2* rp = WS{P.ws}.rope() + (long)pos * 32;
; #pragma unroll
;   for (int r4 = 0; r4 < 4; ++r4) {
;     const int i = r4 * 8 + hi * 4;
;     const float4 g1 = *reinterpret_cast<const float4*>(g + 128 + i), g2 = *reinterpret_cast<const float4*>(g + 160 + i);
;     const float4 cs01 = *reinterpret_cast<const float4*>(rp + i), cs23 = *reinterpret_cast<const float4*>(rp + i + 2);
;     const float x1[4] = {kr[0][r4].x * inv * g1.x, kr[0][r4].y * inv * g1.y, kr[0][r4].z * inv * g1.z, kr[0][r4].w * inv * g1.w};
;     const float x2[4] = {kr[1][r4].x * inv * g2.x, kr[1][r4].y * inv * g2.y, kr[1][r4].z * inv * g2.z, kr[1][r4].w * inv * g2.w};
;     const float cc[4] = {cs01.x, cs01.z, cs23.x, cs23.z}, sn[4] = {cs01.y, cs01.w, cs23.y, cs23.w};
;     st4lds(dst, 128 + i, x1[0] * cc[0] - x2[0] * sn[0], x1[1] * cc[1] - x2[1] * sn[1], x1[2] * cc[2] - x2[2] * sn[2], x1[3] * cc[3] - x2[3] * sn[3]);
;     st4lds(dst, 160 + i, x1[0] * sn[0] + x2[0] * cc[0], x1[1] * sn[1] + x2[1] * cc[1], x1[2] * sn[2] + x2[2] * cc[2], x1[3] * sn[3] + x2[3] * cc[3]);
;   }
;   slab_flush<24, 400>(slab, WS{P.ws}.KB() + (long)(m0 + wid * 32) * 768 + head * 192, 768, hi * 32 + r32);
	v_mov_b32_e32 v50, v0
	v_mov_b32_e32 v51, v4
	v_mov_b32_e32 v4, v1
	v_mov_b32_e32 v0, v2
	v_mov_b32_e32 v1, v6
	v_mov_b32_e32 v6, v3
	v_pk_mul_f32 v[2:3], v[34:35], v[50:51]
	v_pk_mul_f32 v[4:5], v[16:17], v[4:5]
	v_pk_mul_f32 v[0:1], v[32:33], v[0:1]
	v_pk_mul_f32 v[6:7], v[18:19], v[6:7]
	v_pk_mul_f32 v[16:17], v[2:3], v[8:9]
	v_pk_mul_f32 v[18:19], v[4:5], v[10:11]
	v_pk_mul_f32 v[32:33], v[0:1], v[12:13]
	v_pk_mul_f32 v[34:35], v[6:7], v[14:15]
	v_pk_mul_f32 v[2:3], v[2:3], v[8:9] op_sel:[1,0] op_sel_hi:[0,1]
	v_pk_mul_f32 v[4:5], v[4:5], v[10:11] op_sel:[1,0] op_sel_hi:[0,1]
	v_pk_mul_f32 v[0:1], v[0:1], v[12:13] op_sel:[1,0] op_sel_hi:[0,1]
	v_pk_mul_f32 v[6:7], v[6:7], v[14:15] op_sel:[1,0] op_sel_hi:[0,1]
	v_sub_f32_e32 v8, v16, v17
	v_sub_f32_e32 v9, v18, v19
	v_sub_f32_e32 v10, v32, v33
	v_sub_f32_e32 v11, v34, v35
	v_add_f32_e32 v2, v2, v3
	v_add_f32_e32 v3, v4, v5
	v_add_f32_e32 v4, v0, v1
	v_cvt_pk_bf16_f32 v0, v8, v9
	v_cvt_pk_bf16_f32 v1, v10, v11
	v_add_f32_e32 v5, v6, v7
	ds_write_b64 v25, v[0:1] offset:304
	v_cvt_pk_bf16_f32 v0, v2, v3
	v_cvt_pk_bf16_f32 v1, v4, v5
	ds_write_b64 v25, v[0:1] offset:368
	s_waitcnt lgkmcnt(0)
	ds_read_b128 v[0:3], v61
	v_lshl_add_u64 v[4:5], v[20:21], 0, v[184:185]
	v_lshl_add_u64 v[4:5], v[40:41], 1, v[4:5]
	v_lshlrev_b32_e32 v184, 1, v71
	v_add3_u32 v6, v153, v68, v69
	s_waitcnt lgkmcnt(0)
	flat_store_dwordx4 v[4:5], v[0:3]
	ds_read_b128 v[0:3], v70
	v_lshl_add_u64 v[4:5], v[20:21], 0, v[184:185]
	v_lshl_add_u64 v[4:5], v[22:23], 1, v[4:5]
	v_lshlrev_b32_e32 v184, 1, v43
	v_add3_u32 v7, v153, v72, v73
	s_waitcnt lgkmcnt(0)
	flat_store_dwordx4 v[4:5], v[0:3]
	ds_read_b128 v[0:3], v62
	v_lshl_add_u64 v[4:5], v[20:21], 0, v[184:185]
	v_lshl_add_u64 v[4:5], v[26:27], 1, v[4:5]
	v_lshlrev_b32_e32 v184, 1, v53
	v_ashrrev_i32_e32 v43, 31, v42
	s_waitcnt lgkmcnt(0)
	flat_store_dwordx4 v[4:5], v[0:3]
	ds_read_b128 v[0:3], v63
	v_lshl_add_u64 v[4:5], v[20:21], 0, v[184:185]
	v_lshl_add_u64 v[4:5], v[28:29], 1, v[4:5]
	v_lshlrev_b32_e32 v184, 1, v45
	v_add3_u32 v8, v153, v74, v75
	s_waitcnt lgkmcnt(0)
	flat_store_dwordx4 v[4:5], v[0:3]
	ds_read_b128 v[0:3], v64
	v_lshl_add_u64 v[4:5], v[20:21], 0, v[184:185]
	v_lshl_add_u64 v[4:5], v[30:31], 1, v[4:5]
	v_lshlrev_b32_e32 v184, 1, v47
	v_ashrrev_i32_e32 v45, 31, v44
	s_waitcnt lgkmcnt(0)
	flat_store_dwordx4 v[4:5], v[0:3]
	ds_read_b128 v[0:3], v66
	v_lshl_add_u64 v[4:5], v[20:21], 0, v[184:185]
	v_lshl_add_u64 v[4:5], v[36:37], 1, v[4:5]
	v_lshlrev_b32_e32 v184, 1, v54
	v_ashrrev_i32_e32 v47, 31, v46
	s_waitcnt lgkmcnt(0)
	flat_store_dwordx4 v[4:5], v[0:3]
	ds_read_b128 v[0:3], v6
	v_lshl_add_u64 v[4:5], v[20:21], 0, v[184:185]
	v_lshl_add_u64 v[4:5], v[38:39], 1, v[4:5]
	v_lshlrev_b32_e32 v184, 1, v49
	v_add3_u32 v6, v153, v76, v77
	s_waitcnt lgkmcnt(0)
	flat_store_dwordx4 v[4:5], v[0:3]
	ds_read_b128 v[0:3], v7
	v_lshl_add_u64 v[4:5], v[20:21], 0, v[184:185]
	v_lshl_add_u64 v[4:5], v[42:43], 1, v[4:5]
	v_lshlrev_b32_e32 v184, 1, v55
	v_add3_u32 v7, v153, v56, v78
	s_waitcnt lgkmcnt(0)
	flat_store_dwordx4 v[4:5], v[0:3]
	ds_read_b128 v[0:3], v8
	v_lshl_add_u64 v[4:5], v[20:21], 0, v[184:185]
	v_lshl_add_u64 v[4:5], v[44:45], 1, v[4:5]
	v_lshlrev_b32_e32 v184, 1, v57
	v_ashrrev_i32_e32 v49, 31, v48
	s_waitcnt lgkmcnt(0)
	flat_store_dwordx4 v[4:5], v[0:3]
	ds_read_b128 v[0:3], v6
	v_lshl_add_u64 v[4:5], v[20:21], 0, v[184:185]
	v_lshl_add_u64 v[4:5], v[46:47], 1, v[4:5]
	v_lshlrev_b32_e32 v184, 1, v58
	v_add3_u32 v6, v153, v59, v79
	s_waitcnt lgkmcnt(0)
	flat_store_dwordx4 v[4:5], v[0:3]
	ds_read_b128 v[0:3], v7
	v_lshl_add_u64 v[4:5], v[20:21], 0, v[184:185]
	v_lshl_add_u64 v[4:5], v[48:49], 1, v[4:5]
	v_lshlrev_b32_e32 v184, 1, v60
	s_waitcnt lgkmcnt(0)
	flat_store_dwordx4 v[4:5], v[0:3]
	ds_read_b128 v[0:3], v6
	v_lshlrev_b32_e32 v6, 3, v52
	v_lshl_add_u64 v[4:5], v[20:21], 0, v[184:185]
	v_ashrrev_i32_e32 v7, 31, v6
	v_lshl_add_u64 v[4:5], v[6:7], 1, v[4:5]
	s_waitcnt lgkmcnt(0)
	flat_store_dwordx4 v[4:5], v[0:3]
	s_waitcnt lgkmcnt(0)
	s_waitcnt lgkmcnt(0)
	s_barrier
	s_branch .LBB0_355
